# speedup vs baseline: 1.0072x; 1.0072x over previous
; DI unsigned pack2(float a, float b) { f2_t v = {a, b}; bf2_t r = __builtin_convertvector(v, bf2_t); return __builtin_bit_cast(unsigned, r); }
; DI void phase_prep(const Params& p, char* smem) {
;     ...
;         for (int row = wv; row < T_; row += nw) {
;             const float4* hp = (const float4*)(p.in[0] + (size_t)row * 1024);
;             float ss = 0.f;
; #pragma unroll
;             for (int i = 0; i < 4; ++i) {
;                 const float4 v = hp[lane + 64 * i];
;                 ss += v.x * v.x + v.y * v.y + v.z * v.z + v.w * v.w;
;                 uint2 o;
;                 o.x = pack2(v.x, v.y);
;                 o.y = pack2(v.z, v.w);
;                 *(uint2*)(h16 + (size_t)row * 1024 + (lane + 64 * i) * 4) = o;
;             }
;             ss = wave_sum(ss);
;             if (lane < 16) ssq[(size_t)row * 16 + lane] = lane == 0 ? ss : 0.f;
;         }
.LBB0_368:
	global_load_dwordx4 v[14:17], v[6:7], off
	global_load_dwordx4 v[18:21], v[6:7], off offset:1024
	global_load_dwordx4 v[22:25], v[6:7], off offset:2048
	global_load_dwordx4 v[26:29], v[6:7], off offset:3072
	v_lshl_add_u64 v[36:37], s[92:93], 0, v[4:5]
	v_add_co_u32_e64 v30, s[4:5], s7, v36
	s_nop 1
	v_addc_co_u32_e64 v31, s[4:5], 0, v37, s[4:5]
	s_waitcnt vmcnt(0)
	v_cvt_pk_bf16_f32 v38, v14, v15
	v_cvt_pk_bf16_f32 v39, v16, v17
	global_store_dwordx2 v[30:31], v[38:39], off
	v_mul_f32_e32 v32, v15, v15
	v_pk_fma_f32 v[14:15], v[14:15], v[14:15], v[32:33] op_sel_hi:[1,1,0]
	v_mul_f32_e32 v34, v17, v17
	v_pk_fma_f32 v[14:15], v[16:17], v[16:17], v[14:15]
	v_cvt_pk_bf16_f32 v40, v18, v19
	v_cvt_pk_bf16_f32 v41, v20, v21
	global_store_dwordx2 v[30:31], v[40:41], off offset:512
	v_mul_f32_e32 v16, v19, v19
	v_pk_fma_f32 v[16:17], v[18:19], v[18:19], v[16:17] op_sel_hi:[1,1,0]
	v_mul_f32_e32 v32, v21, v21
	v_pk_fma_f32 v[16:17], v[20:21], v[20:21], v[16:17]
	v_pk_add_f32 v[14:15], v[14:15], v[34:35] op_sel_hi:[1,0]
	v_pk_add_f32 v[16:17], v[16:17], v[32:33] op_sel_hi:[1,0]
	v_cvt_pk_bf16_f32 v42, v22, v23
	v_cvt_pk_bf16_f32 v43, v24, v25
	global_store_dwordx2 v[30:31], v[42:43], off offset:1024
	v_pk_add_f32 v[14:15], v[14:15], v[16:17]
	v_mul_f32_e32 v16, v23, v23
	v_pk_fma_f32 v[16:17], v[22:23], v[22:23], v[16:17] op_sel_hi:[1,1,0]
	v_mul_f32_e32 v18, v25, v25
	v_pk_fma_f32 v[16:17], v[24:25], v[24:25], v[16:17]
	s_nop 0
	v_pk_add_f32 v[16:17], v[16:17], v[18:19] op_sel_hi:[1,0]
	v_mul_f32_e32 v18, v29, v29
	v_pk_add_f32 v[14:15], v[14:15], v[16:17]
	v_mul_f32_e32 v16, v27, v27
	v_pk_fma_f32 v[16:17], v[26:27], v[26:27], v[16:17] op_sel_hi:[1,1,0]
	s_nop 0
	v_pk_fma_f32 v[16:17], v[28:29], v[28:29], v[16:17]
	s_nop 0
	v_pk_add_f32 v[16:17], v[16:17], v[18:19] op_sel_hi:[1,0]
	s_nop 0
	v_pk_add_f32 v[14:15], v[14:15], v[16:17]
	s_nop 0
	v_mov_b32_e32 v1, v14
	s_nop 1
	v_permlane32_swap_b32_e32 v14, v1
	v_add_f32_e32 v1, v14, v1
	s_waitcnt lgkmcnt(0)
	ds_bpermute_b32 v13, v8, v1
	v_cvt_pk_bf16_f32 v14, v26, v27
	v_cvt_pk_bf16_f32 v15, v28, v29
	global_store_dwordx2 v[30:31], v[14:15], off offset:1536
	s_waitcnt lgkmcnt(0)
	v_add_f32_e32 v1, v1, v13
	ds_bpermute_b32 v13, v9, v1
	s_waitcnt lgkmcnt(0)
	v_add_f32_e32 v1, v1, v13
	ds_bpermute_b32 v13, v10, v1
	s_waitcnt lgkmcnt(0)
	v_add_f32_e32 v1, v1, v13
	ds_bpermute_b32 v13, v11, v1
	s_waitcnt lgkmcnt(0)
	v_add_f32_e32 v1, v1, v13
	ds_bpermute_b32 v13, v12, v1
	s_and_saveexec_b64 s[4:5], vcc
	s_cbranch_execz .LBB0_367
	s_waitcnt lgkmcnt(0)
	v_add_f32_e32 v1, v1, v13
	v_cndmask_b32_e64 v1, 0, v1, s[2:3]
	v_lshl_add_u64 v[14:15], s[92:93], 0, v[2:3]
	global_store_dword v[14:15], v1, off
	s_branch .LBB0_367

; DI void phase_gate(const Params& p, int l_idx, char* smem) {
;     ...
;         for (int j = 0; j < own; ++j) {
;             float dot = 0.f;
; #pragma unroll
;             for (int d = 0; d < 64; ++d) dot += qv[d] * km[j * 64 + d];
;             if (dot > v0) { v2 = v1; i2 = i1; v1 = v0; i1 = i0; v0 = dot; i0 = j; }
;             else if (dot > v1) { v2 = v1; i2 = i1; v1 = dot; i1 = j; }
;             else if (dot > v2) { v2 = dot; i2 = j; }
;         }
.LBB0_648:
	s_add_u32 s12, s9, s10
	s_addc_u32 s13, s23, s11
	s_add_u32 s14, s12, 0x16888000
	s_addc_u32 s15, s13, 0
	global_load_dwordx4 v[74:77], v1, s[14:15] offset:48
	global_load_dwordx4 v[78:81], v1, s[14:15] offset:32
	global_load_dwordx4 v[82:85], v1, s[14:15] offset:16
	global_load_dwordx4 v[86:89], v200, s[12:13]
	s_add_u32 s14, s12, 0x16888040
	s_addc_u32 s15, s13, 0
	global_load_dwordx4 v[92:95], v1, s[14:15] offset:48
	global_load_dwordx4 v[96:99], v1, s[14:15] offset:32
	global_load_dwordx4 v[100:103], v1, s[14:15] offset:16
	global_load_dwordx4 v[104:107], v200, s[12:13] offset:64
	s_add_u32 s14, s12, 0x16888080
	s_addc_u32 s15, s13, 0
	global_load_dwordx4 v[108:111], v1, s[14:15] offset:48
	global_load_dwordx4 v[112:115], v1, s[14:15] offset:32
	global_load_dwordx4 v[116:119], v1, s[14:15] offset:16
	global_load_dwordx4 v[120:123], v200, s[12:13] offset:128
	s_add_u32 s14, s12, 0x168880c0
	s_addc_u32 s15, s13, 0
	global_load_dwordx4 v[124:127], v200, s[12:13] offset:192
	global_load_dwordx4 v[128:131], v1, s[14:15] offset:48
	global_load_dwordx4 v[132:135], v1, s[14:15] offset:32
	global_load_dwordx4 v[136:139], v1, s[14:15] offset:16
	s_waitcnt vmcnt(12)
	v_fma_f32 v90, v86, v16, 0
	v_fmac_f32_e32 v90, v87, v17
	v_fmac_f32_e32 v90, v88, v18
	v_fmac_f32_e32 v90, v89, v19
	v_fmac_f32_e32 v90, v82, v20
	v_fmac_f32_e32 v90, v83, v21
	v_fmac_f32_e32 v90, v84, v22
	v_fmac_f32_e32 v90, v85, v23
	v_fmac_f32_e32 v90, v78, v24
	v_fmac_f32_e32 v90, v79, v25
	v_fmac_f32_e32 v90, v80, v26
	v_fmac_f32_e32 v90, v81, v27
	v_fmac_f32_e32 v90, v74, v28
	v_fmac_f32_e32 v90, v75, v29
	v_fmac_f32_e32 v90, v76, v30
	v_fmac_f32_e32 v90, v77, v31
	s_waitcnt vmcnt(8)
	v_fmac_f32_e32 v90, v104, v32
	v_fmac_f32_e32 v90, v105, v33
	v_fmac_f32_e32 v90, v106, v34
	v_fmac_f32_e32 v90, v107, v35
	v_fmac_f32_e32 v90, v100, v36
	v_fmac_f32_e32 v90, v101, v37
	v_fmac_f32_e32 v90, v102, v38
	v_fmac_f32_e32 v90, v103, v39
	v_fmac_f32_e32 v90, v96, v40
	v_fmac_f32_e32 v90, v97, v41
	v_fmac_f32_e32 v90, v98, v42
	v_fmac_f32_e32 v90, v99, v43
	v_fmac_f32_e32 v90, v92, v44
	v_fmac_f32_e32 v90, v93, v45
	v_fmac_f32_e32 v90, v94, v46
	v_fmac_f32_e32 v90, v95, v47
	s_waitcnt vmcnt(4)
	v_fmac_f32_e32 v90, v120, v48
	v_fmac_f32_e32 v90, v121, v49
	v_fmac_f32_e32 v90, v122, v50
	v_fmac_f32_e32 v90, v123, v51
	v_fmac_f32_e32 v90, v116, v52
	v_fmac_f32_e32 v90, v117, v53
	v_fmac_f32_e32 v90, v118, v54
	v_fmac_f32_e32 v90, v119, v55
	v_fmac_f32_e32 v90, v112, v56
	v_fmac_f32_e32 v90, v113, v57
	v_fmac_f32_e32 v90, v114, v58
	v_fmac_f32_e32 v90, v115, v59
	v_fmac_f32_e32 v90, v108, v60
	v_fmac_f32_e32 v90, v109, v61
	v_fmac_f32_e32 v90, v110, v62
	v_fmac_f32_e32 v90, v111, v63
	s_waitcnt vmcnt(3)
	v_fmac_f32_e32 v90, v124, v64
	v_fmac_f32_e32 v90, v125, v65
	v_fmac_f32_e32 v90, v126, v66
	v_fmac_f32_e32 v90, v127, v67
	s_waitcnt vmcnt(0)
	v_pk_mul_f32 v[74:75], v[136:137], v[4:5]
	s_nop 0
	v_add_f32_e32 v74, v90, v74
	v_add_f32_e32 v76, v74, v75
	v_pk_mul_f32 v[74:75], v[138:139], v[6:7]
	s_nop 0
	v_add_f32_e32 v74, v76, v74
	v_add_f32_e32 v76, v74, v75
	v_pk_mul_f32 v[74:75], v[132:133], v[8:9]
	s_nop 0
	v_add_f32_e32 v74, v76, v74
	v_add_f32_e32 v76, v74, v75
	v_pk_mul_f32 v[74:75], v[134:135], v[10:11]
	s_nop 0
	v_add_f32_e32 v74, v76, v74
	v_add_f32_e32 v76, v74, v75
	v_pk_mul_f32 v[74:75], v[128:129], v[12:13]
	s_nop 0
	v_add_f32_e32 v74, v76, v74
	v_add_f32_e32 v76, v74, v75
	v_pk_mul_f32 v[74:75], v[130:131], v[14:15]
	s_nop 0
	v_add_f32_e32 v74, v76, v74
	v_add_f32_e32 v74, v74, v75
	v_cmp_ngt_f32_e32 vcc, v74, v71
	v_mov_b32_e32 v75, s36
	s_and_saveexec_b64 s[12:13], vcc
	s_cbranch_execz .LBB0_654
	v_cmp_ngt_f32_e32 vcc, v74, v70
	v_mov_b32_e32 v76, s36
	s_and_saveexec_b64 s[14:15], vcc
	s_cbranch_execz .LBB0_653
	v_cmp_gt_f32_e32 vcc, v74, v73
	s_and_saveexec_b64 s[16:17], vcc
	v_mov_b32_e32 v72, s36
	v_mov_b32_e32 v73, v74
	s_or_b64 exec, exec, s[16:17]
	v_mov_b32_e32 v76, v68
	v_mov_b32_e32 v74, v70
	v_mov_b32_e32 v70, v73
	v_mov_b32_e32 v68, v72

; #define MFMA(a, b, c) __builtin_amdgcn_mfma_f32_32x32x16_bf16((a), (b), (c), 0, 0, 0)
;     ...
;             auto qk = [&](const int sub, f32x16 (&st)[QS]) {
; #pragma unroll
;                 for (int qs = 0; qs < QS; ++qs) zero_acc(st[qs]);
; #pragma unroll
;                 for (int s = 0; s < DQK / 16; ++s) {
;                     bf16x8 kf;
;                     if (DQK == 64) kf = *(const bf16x8*)(sK + sub * 4096 + (klane ^ (s << 5)));
;                     else kf = *(const bf16x8*)(sK + sub * 6144 + klane + s * 32 + (s == 4 ? wrap4 : s == 5 ? wrap5 : 0));
; #pragma unroll
;                     for (int qs = 0; qs < QS; ++qs) st[qs] = MFMA(kf, qf[qs][s], st[qs]);
;                 }
.LBB0_846:
	v_cmp_ne_u32_e32 vcc, 0, v6
	s_and_saveexec_b64 s[10:11], vcc
	s_cbranch_execz .LBB0_1000
	v_add_u32_e32 v5, s14, v226
	ds_read_b128 v[8:11], v5
	v_add_u32_e32 v4, s14, v227
	v_add_u32_e32 v3, s14, v228
	v_add_u32_e32 v2, s14, v229
	s_and_b32 s62, s63, 31
	v_cmp_eq_u32_e64 s[42:43], 3, v6
	s_waitcnt lgkmcnt(0)
	v_mfma_f32_32x32x16_bf16 v[96:111], v[8:11], v[128:131], 0
	v_mfma_f32_32x32x16_bf16 v[80:95], v[8:11], v[144:147], 0
	ds_read_b128 v[240:243], v4
	ds_read_b128 v[236:239], v3
	ds_read_b128 v[8:11], v2
	s_waitcnt lgkmcnt(2)
	v_mfma_f32_32x32x16_bf16 v[96:111], v[240:243], v[132:135], v[96:111]
	v_mfma_f32_32x32x16_bf16 v[80:95], v[240:243], v[148:151], v[80:95]
	s_waitcnt lgkmcnt(1)
	v_mfma_f32_32x32x16_bf16 v[96:111], v[236:239], v[136:139], v[96:111]
	v_mfma_f32_32x32x16_bf16 v[80:95], v[236:239], v[152:155], v[80:95]
	s_waitcnt lgkmcnt(0)
	v_mfma_f32_32x32x16_bf16 v[96:111], v[8:11], v[140:143], v[96:111]
	v_mfma_f32_32x32x16_bf16 v[80:95], v[8:11], v[156:159], v[80:95]
	s_and_saveexec_b64 s[12:13], s[42:43]
	s_cbranch_execz .LBB0_861
	s_cmp_lt_i32 s71, 1
	s_cbranch_scc1 .LBB0_853
	s_cmp_gt_i32 s71, 1
	s_cbranch_scc0 .LBB0_854
	s_cmp_eq_u32 s71, 2
	s_mov_b64 s[14:15], -1
	s_cbranch_scc0 .LBB0_852
	s_mov_b64 s[14:15], 0

; #define MFMA(a, b, c) __builtin_amdgcn_mfma_f32_32x32x16_bf16((a), (b), (c), 0, 0, 0)
;     ...
;             auto qk = [&](const int sub, f32x16 (&st)[QS]) {
; #pragma unroll
;                 for (int qs = 0; qs < QS; ++qs) zero_acc(st[qs]);
; #pragma unroll
;                 for (int s = 0; s < DQK / 16; ++s) {
;                     bf16x8 kf;
;                     if (DQK == 64) kf = *(const bf16x8*)(sK + sub * 4096 + (klane ^ (s << 5)));
;                     else kf = *(const bf16x8*)(sK + sub * 6144 + klane + s * 32 + (s == 4 ? wrap4 : s == 5 ? wrap5 : 0));
; #pragma unroll
;                     for (int qs = 0; qs < QS; ++qs) st[qs] = MFMA(kf, qf[qs][s], st[qs]);
;                 }
;             };
;             auto sm_pv = [&](const int sub, f32x16 (&st)[QS]) {
; #pragma unroll
;                 for (int qs = 0; qs < QS; ++qs) {
;                     bool exact = true;
;                     if ((QS == 1 || DQK == 96 || Pol::FASTEXP) && mode == 1 && __all(seen[qs] && (m[qs] == 0.f))) {
;                         float ps = 0.f;
; #pragma unroll
;                         for (int r = 0; r < 16; ++r) {
;                             const float pv = __builtin_amdgcn_exp2f(st[qs][r]);
;                             st[qs][r] = pv;
;                             ps += pv;
;                         }
;                         if (!__any(!(ps < 1048576.f))) {
;                             l[qs] += ps;
;                             exact = false;
;                         } else {
;                             asm volatile("" ::: "memory");
;                             zero_acc(st[qs]);
; #pragma unroll
;                             for (int s = 0; s < DQK / 16; ++s) {
;                                 bf16x8 kf;
;                                 if (DQK == 64) kf = *(const bf16x8*)(sK + sub * 4096 + (klane ^ (s << 5)));
;                                 else kf = *(const bf16x8*)(sK + sub * 6144 + klane + s * 32 + (s == 4 ? wrap4 : s == 5 ? wrap5 : 0));
;                                 st[qs] = MFMA(kf, qf[qs][s], st[qs]);
;                             }
;                         }
.LBB0_1166:
	v_add_u32_e32 v15, s63, v179
	s_waitcnt vmcnt(0)
	ds_read_b128 v[2:5], v15
	v_add_u32_e32 v189, v15, v184
	ds_read_b128 v[226:229], v189 offset:160
	v_add_u32_e32 v188, v15, v183
	s_add_i32 s0, s8, 0xffffffbf
	v_cmp_gt_i32_e64 s[16:17], s0, v173
	v_cmp_le_i32_e64 s[0:1], s0, v173
	s_mov_b64 s[44:45], s[16:17]
	s_waitcnt lgkmcnt(0)
	v_mfma_f32_32x32x16_bf16 v[96:111], v[2:5], v[112:115], 0
	v_mfma_f32_32x32x16_bf16 v[80:95], v[2:5], v[136:139], 0
	ds_read_b128 v[2:5], v15 offset:32
	ds_read_b128 v[238:241], v15 offset:64
	ds_read_b128 v[234:237], v15 offset:96
	s_waitcnt lgkmcnt(2)
	v_mfma_f32_32x32x16_bf16 v[96:111], v[2:5], v[116:119], v[96:111]
	v_mfma_f32_32x32x16_bf16 v[80:95], v[2:5], v[140:143], v[80:95]
	ds_read_b128 v[2:5], v188 offset:128
	s_waitcnt lgkmcnt(2)
	v_mfma_f32_32x32x16_bf16 v[96:111], v[238:241], v[120:123], v[96:111]
	v_mfma_f32_32x32x16_bf16 v[80:95], v[238:241], v[144:147], v[80:95]
	s_waitcnt lgkmcnt(1)
	v_mfma_f32_32x32x16_bf16 v[96:111], v[234:237], v[124:127], v[96:111]
	v_mfma_f32_32x32x16_bf16 v[80:95], v[234:237], v[148:151], v[80:95]
	s_waitcnt lgkmcnt(0)
	v_mfma_f32_32x32x16_bf16 v[96:111], v[2:5], v[128:131], v[96:111]
	v_mfma_f32_32x32x16_bf16 v[80:95], v[2:5], v[152:155], v[80:95]
	v_mfma_f32_32x32x16_bf16 v[96:111], v[226:229], v[132:135], v[96:111]
	v_mfma_f32_32x32x16_bf16 v[80:95], v[226:229], v[156:159], v[80:95]
	s_and_saveexec_b64 s[36:37], s[0:1]
	s_cbranch_execz .LBB0_1173
	v_cmp_eq_f32_e32 vcc, 0, v0
	s_and_b64 s[18:19], s[10:11], vcc
	v_cndmask_b32_e64 v2, 0, 1, s[18:19]
	v_cmp_ne_u32_e32 vcc, 0, v2
	s_cmp_eq_u64 vcc, exec
	s_mov_b64 s[38:39], -1
	s_cbranch_scc0 .LBB0_1170
	s_nop 1
	v_exp_f32_e32 v2, v96
	v_exp_f32_e32 v3, v97
	v_exp_f32_e32 v4, v98
	v_exp_f32_e32 v5, v99
	v_add_f32_e32 v6, 0, v2
	v_add_f32_e32 v6, v3, v6
	v_add_f32_e32 v6, v4, v6
	v_add_f32_e32 v10, v5, v6
	v_exp_f32_e32 v6, v100
	v_exp_f32_e32 v7, v101
	v_exp_f32_e32 v8, v102
	v_exp_f32_e32 v9, v103
	v_add_f32_e32 v10, v6, v10
	v_add_f32_e32 v10, v7, v10
	v_add_f32_e32 v10, v8, v10
	v_add_f32_e32 v96, v9, v10
	v_exp_f32_e32 v10, v104
	v_exp_f32_e32 v11, v105
	v_exp_f32_e32 v12, v106
	v_exp_f32_e32 v13, v107
	v_add_f32_e32 v96, v10, v96
	v_exp_f32_e32 v191, v108
	v_add_f32_e32 v96, v11, v96
	v_exp_f32_e32 v193, v109
	v_add_f32_e32 v96, v12, v96
	v_exp_f32_e32 v194, v110
	v_add_f32_e32 v96, v13, v96
	v_exp_f32_e32 v195, v111
	v_add_f32_e32 v96, v191, v96
	v_add_f32_e32 v96, v193, v96
	v_add_f32_e32 v96, v194, v96
	v_add_f32_e32 v192, v195, v96
	v_cmp_ngt_f32_e32 vcc, s25, v192
	s_cbranch_vccz .LBB0_1171
	ds_read_b128 v[96:99], v15
	ds_read_b128 v[226:229], v15 offset:32
	s_waitcnt lgkmcnt(1)
	v_mfma_f32_32x32x16_bf16 v[96:111], v[96:99], v[112:115], 0
	s_waitcnt lgkmcnt(0)
	v_mfma_f32_32x32x16_bf16 v[96:111], v[226:229], v[116:119], v[96:111]
	ds_read_b128 v[226:229], v15 offset:64
	s_waitcnt lgkmcnt(0)
	v_mfma_f32_32x32x16_bf16 v[96:111], v[226:229], v[120:123], v[96:111]
	ds_read_b128 v[226:229], v15 offset:96
	s_waitcnt lgkmcnt(0)
	v_mfma_f32_32x32x16_bf16 v[96:111], v[226:229], v[124:127], v[96:111]
	ds_read_b128 v[226:229], v188 offset:128
	s_waitcnt lgkmcnt(0)
	v_mfma_f32_32x32x16_bf16 v[96:111], v[226:229], v[128:131], v[96:111]
	ds_read_b128 v[226:229], v189 offset:160
	s_waitcnt lgkmcnt(0)
	v_mfma_f32_32x32x16_bf16 v[96:111], v[226:229], v[132:135], v[96:111]
	s_branch .LBB0_1172

;     ...
;                 for (int s = 0; s < DQK / 16; ++s) {
;                     bf16x8 kf;
;                     if (DQK == 64) kf = *(const bf16x8*)(sK + sub * 4096 + (klane ^ (s << 5)));
;                     else kf = *(const bf16x8*)(sK + sub * 6144 + klane + s * 32 + (s == 4 ? wrap4 : s == 5 ? wrap5 : 0));
; #pragma unroll
;                     for (int qs = 0; qs < QS; ++qs) st[qs] = MFMA(kf, qf[qs][s], st[qs]);
;                 }
;             };
;             auto sm_pv = [&](const int sub, f32x16 (&st)[QS]) {
; #pragma unroll
;                 for (int qs = 0; qs < QS; ++qs) {
;                     bool exact = true;
;                     if ((QS == 1 || DQK == 96 || Pol::FASTEXP) && mode == 1 && __all(seen[qs] && (m[qs] == 0.f))) {
;                         float ps = 0.f;
; #pragma unroll
;                         for (int r = 0; r < 16; ++r) {
;                             const float pv = __builtin_amdgcn_exp2f(st[qs][r]);
;                             st[qs][r] = pv;
;                             ps += pv;
;                         }
;                         if (!__any(!(ps < 1048576.f))) {
;                             l[qs] += ps;
;                             exact = false;
;                         } else {
;                             asm volatile("" ::: "memory");
;                             zero_acc(st[qs]);
; #pragma unroll
;                             for (int s = 0; s < DQK / 16; ++s) {
;                                 bf16x8 kf;
;                                 if (DQK == 64) kf = *(const bf16x8*)(sK + sub * 4096 + (klane ^ (s << 5)));
;                                 else kf = *(const bf16x8*)(sK + sub * 6144 + klane + s * 32 + (s == 4 ? wrap4 : s == 5 ? wrap5 : 0));
;                                 st[qs] = MFMA(kf, qf[qs][s], st[qs]);
;                             }
;                         }
;     ...
;                     for (int s2 = 0; s2 < 2; ++s2) {
;                         union { unsigned u[4]; bf16x8 v; } pk;
; #pragma unroll
;                         for (int q = 0; q < 4; ++q) pk.u[q] = pack2(st[qs][8 * s2 + 2 * q], st[qs][8 * s2 + 2 * q + 1]);
; #pragma unroll
;                         for (int t = 0; t < DV / 32; ++t) {
;                             const bf16x8 vf = *(const bf16x8*)(sV + t * 4096 + (vlane ^ ((4 * sub + 2 * s2) << 4)));
;                             o[qs][t] = MFMA(vf, pk.v, o[qs][t]);
.LBB0_1208:
	s_or_b64 exec, exec, s[44:45]
	s_nop 2
	v_cvt_pk_bf16_f32 v80, v102, v103
	v_cvt_pk_bf16_f32 v81, v104, v105
	v_cvt_pk_bf16_f32 v82, v106, v107
	v_cvt_pk_bf16_f32 v83, v108, v110
	s_mov_b64 s[48:49], s[16:17]
	ds_read_b128 v[228:231], v189 offset:6304
	s_waitcnt lgkmcnt(4)
	v_mfma_f32_32x32x16_bf16 v[32:47], v[2:5], v[80:83], v[32:47]
	v_cvt_pk_bf16_f32 v2, v109, v111
	v_cvt_pk_bf16_f32 v3, v193, v194
	v_cvt_pk_bf16_f32 v4, v195, v225
	v_cvt_pk_bf16_f32 v5, v226, v227
	s_waitcnt lgkmcnt(3)
	v_mfma_f32_32x32x16_bf16 v[16:31], v[6:9], v[80:83], v[16:31]
	s_waitcnt lgkmcnt(2)
	v_mfma_f32_32x32x16_bf16 v[32:47], v[10:13], v[2:5], v[32:47]
	s_waitcnt lgkmcnt(1)
	v_mfma_f32_32x32x16_bf16 v[16:31], v[96:99], v[2:5], v[16:31]
	ds_read_b128 v[234:237], v15 offset:6144
	ds_read_b128 v[2:5], v15 offset:6176
	ds_read_b128 v[238:241], v15 offset:6208
	s_waitcnt lgkmcnt(2)
	v_mfma_f32_32x32x16_bf16 v[96:111], v[234:237], v[112:115], 0
	v_mfma_f32_32x32x16_bf16 v[80:95], v[234:237], v[136:139], 0
	ds_read_b128 v[234:237], v15 offset:6240
	s_waitcnt lgkmcnt(2)
	v_mfma_f32_32x32x16_bf16 v[96:111], v[2:5], v[116:119], v[96:111]
	v_mfma_f32_32x32x16_bf16 v[80:95], v[2:5], v[140:143], v[80:95]
	ds_read_b128 v[2:5], v188 offset:6272
	s_waitcnt lgkmcnt(2)
	v_mfma_f32_32x32x16_bf16 v[96:111], v[238:241], v[120:123], v[96:111]
	v_mfma_f32_32x32x16_bf16 v[80:95], v[238:241], v[144:147], v[80:95]
	s_waitcnt lgkmcnt(1)
	v_mfma_f32_32x32x16_bf16 v[96:111], v[234:237], v[124:127], v[96:111]
	v_mfma_f32_32x32x16_bf16 v[80:95], v[234:237], v[148:151], v[80:95]
	s_waitcnt lgkmcnt(0)
	v_mfma_f32_32x32x16_bf16 v[96:111], v[2:5], v[128:131], v[96:111]
	v_mfma_f32_32x32x16_bf16 v[80:95], v[2:5], v[152:155], v[80:95]
	v_mfma_f32_32x32x16_bf16 v[96:111], v[228:231], v[132:135], v[96:111]
	v_mfma_f32_32x32x16_bf16 v[80:95], v[228:231], v[156:159], v[80:95]
	s_and_saveexec_b64 s[36:37], s[0:1]
	s_cbranch_execz .LBB0_1215
	v_cmp_eq_f32_e32 vcc, 0, v0
	s_and_b64 s[18:19], s[38:39], vcc
	v_cndmask_b32_e64 v2, 0, 1, s[18:19]
	v_cmp_ne_u32_e32 vcc, 0, v2
	s_cmp_eq_u64 vcc, exec
	s_mov_b64 s[44:45], -1
	s_cbranch_scc0 .LBB0_1212
	s_nop 1
	v_exp_f32_e32 v2, v96
	v_exp_f32_e32 v3, v97
	v_exp_f32_e32 v4, v98
	v_exp_f32_e32 v5, v99
	v_add_f32_e32 v6, 0, v2
	v_add_f32_e32 v6, v3, v6
	v_add_f32_e32 v6, v4, v6
	v_add_f32_e32 v10, v5, v6
	v_exp_f32_e32 v6, v100
	v_exp_f32_e32 v7, v101
	v_exp_f32_e32 v8, v102
	v_exp_f32_e32 v9, v103
	v_add_f32_e32 v10, v6, v10
	v_add_f32_e32 v10, v7, v10
	v_add_f32_e32 v10, v8, v10
	v_add_f32_e32 v96, v9, v10
	v_exp_f32_e32 v10, v104
	v_exp_f32_e32 v11, v105
	v_exp_f32_e32 v12, v106
	v_exp_f32_e32 v13, v107
	v_add_f32_e32 v96, v10, v96
	v_exp_f32_e32 v194, v108
	v_add_f32_e32 v96, v11, v96
	v_exp_f32_e32 v195, v109
	v_add_f32_e32 v96, v12, v96
	v_exp_f32_e32 v225, v110
	v_add_f32_e32 v96, v13, v96
	v_exp_f32_e32 v226, v111
	v_add_f32_e32 v96, v194, v96
	v_add_f32_e32 v96, v195, v96
	v_add_f32_e32 v96, v225, v96
	v_add_f32_e32 v193, v226, v96
	v_cmp_ngt_f32_e32 vcc, s25, v193
	s_cbranch_vccz .LBB0_1213
	ds_read_b128 v[96:99], v15 offset:6144
	ds_read_b128 v[228:231], v15 offset:6176
	s_waitcnt lgkmcnt(1)
	v_mfma_f32_32x32x16_bf16 v[96:111], v[96:99], v[112:115], 0
	s_waitcnt lgkmcnt(0)
	v_mfma_f32_32x32x16_bf16 v[96:111], v[228:231], v[116:119], v[96:111]
	ds_read_b128 v[228:231], v15 offset:6208
	s_waitcnt lgkmcnt(0)
	v_mfma_f32_32x32x16_bf16 v[96:111], v[228:231], v[120:123], v[96:111]
	ds_read_b128 v[228:231], v15 offset:6240
	s_waitcnt lgkmcnt(0)
	v_mfma_f32_32x32x16_bf16 v[96:111], v[228:231], v[124:127], v[96:111]
	ds_read_b128 v[228:231], v188 offset:6272
	s_waitcnt lgkmcnt(0)
	v_mfma_f32_32x32x16_bf16 v[96:111], v[228:231], v[128:131], v[96:111]
	ds_read_b128 v[228:231], v189 offset:6304
	s_waitcnt lgkmcnt(0)
	v_mfma_f32_32x32x16_bf16 v[96:111], v[228:231], v[132:135], v[96:111]
	s_branch .LBB0_1214

; #define MFMA(a, b, c) __builtin_amdgcn_mfma_f32_32x32x16_bf16((a), (b), (c), 0, 0, 0)
;     ...
;             auto qk = [&](const int sub, f32x16 (&st)[QS]) {
; #pragma unroll
;                 for (int qs = 0; qs < QS; ++qs) zero_acc(st[qs]);
; #pragma unroll
;                 for (int s = 0; s < DQK / 16; ++s) {
;                     bf16x8 kf;
;                     if (DQK == 64) kf = *(const bf16x8*)(sK + sub * 4096 + (klane ^ (s << 5)));
;                     else kf = *(const bf16x8*)(sK + sub * 6144 + klane + s * 32 + (s == 4 ? wrap4 : s == 5 ? wrap5 : 0));
; #pragma unroll
;                     for (int qs = 0; qs < QS; ++qs) st[qs] = MFMA(kf, qf[qs][s], st[qs]);
;                 }
;             };
;             auto sm_pv = [&](const int sub, f32x16 (&st)[QS]) {
; #pragma unroll
;                 for (int qs = 0; qs < QS; ++qs) {
;                     bool exact = true;
;                     if ((QS == 1 || DQK == 96 || Pol::FASTEXP) && mode == 1 && __all(seen[qs] && (m[qs] == 0.f))) {
;                         float ps = 0.f;
; #pragma unroll
;                         for (int r = 0; r < 16; ++r) {
;                             const float pv = __builtin_amdgcn_exp2f(st[qs][r]);
;                             st[qs][r] = pv;
;                             ps += pv;
;                         }
;                         if (!__any(!(ps < 1048576.f))) {
;                             l[qs] += ps;
;                             exact = false;
;                         } else {
;                             asm volatile("" ::: "memory");
;                             zero_acc(st[qs]);
; #pragma unroll
;                             for (int s = 0; s < DQK / 16; ++s) {
;                                 bf16x8 kf;
;                                 if (DQK == 64) kf = *(const bf16x8*)(sK + sub * 4096 + (klane ^ (s << 5)));
;                                 else kf = *(const bf16x8*)(sK + sub * 6144 + klane + s * 32 + (s == 4 ? wrap4 : s == 5 ? wrap5 : 0));
;                                 st[qs] = MFMA(kf, qf[qs][s], st[qs]);
;                             }
;                         }
.LBB0_1368:
	s_andn2_b64 s[0:1], s[12:13], exec
	s_and_b64 s[12:13], s[16:17], exec
	v_cmp_le_i32_e32 vcc, s63, v168
	s_or_b64 s[12:13], s[0:1], s[12:13]
	s_and_saveexec_b64 s[38:39], vcc
	s_cbranch_execz .LBB0_1412
	v_add_u32_e32 v4, s19, v173
	s_waitcnt vmcnt(0)
	ds_read_b128 v[6:9], v4
	v_add_u32_e32 v5, s19, v172
	v_add_u32_e32 v3, s19, v170
	v_add_u32_e32 v2, s19, v169
	s_add_i32 s0, s63, 63
	v_cmp_gt_i32_e64 s[42:43], s0, v168
	v_cmp_le_i32_e64 s[0:1], s0, v168
	s_mov_b64 s[56:57], s[42:43]
	s_waitcnt lgkmcnt(0)
	v_mfma_f32_32x32x16_bf16 v[96:111], v[6:9], v[132:135], 0
	ds_read_b128 v[186:189], v5
	ds_read_b128 v[182:185], v3
	ds_read_b128 v[6:9], v2
	ds_read_b128 v[190:193], v4 offset:4096
	s_waitcnt lgkmcnt(3)
	v_mfma_f32_32x32x16_bf16 v[96:111], v[186:189], v[128:131], v[96:111]
	ds_read_b128 v[186:189], v5 offset:4096
	s_waitcnt lgkmcnt(3)
	v_mfma_f32_32x32x16_bf16 v[96:111], v[182:185], v[136:139], v[96:111]
	ds_read_b128 v[182:185], v3 offset:4096
	s_waitcnt lgkmcnt(3)
	v_mfma_f32_32x32x16_bf16 v[96:111], v[6:9], v[140:143], v[96:111]
	ds_read_b128 v[6:9], v2 offset:4096
	s_waitcnt lgkmcnt(3)
	v_mfma_f32_32x32x16_bf16 v[80:95], v[190:193], v[132:135], 0
	s_waitcnt lgkmcnt(2)
	v_mfma_f32_32x32x16_bf16 v[80:95], v[186:189], v[128:131], v[80:95]
	s_waitcnt lgkmcnt(1)
	v_mfma_f32_32x32x16_bf16 v[80:95], v[182:185], v[136:139], v[80:95]
	s_waitcnt lgkmcnt(0)
	v_mfma_f32_32x32x16_bf16 v[80:95], v[6:9], v[140:143], v[80:95]
	s_and_saveexec_b64 s[36:37], s[0:1]
	s_cbranch_execz .LBB0_1376
	v_cmp_eq_f32_e32 vcc, 0, v174
	s_and_b64 s[18:19], s[16:17], vcc
	v_cndmask_b32_e64 v6, 0, 1, s[18:19]
	v_cmp_ne_u32_e32 vcc, 0, v6
	s_cmp_eq_u64 vcc, exec
	s_mov_b64 s[44:45], -1
	s_cbranch_scc0 .LBB0_1373
	v_exp_f32_e32 v112, v96
	v_exp_f32_e32 v113, v97
	v_exp_f32_e32 v114, v98
	v_exp_f32_e32 v115, v99
	v_add_f32_e32 v6, 0, v112
	v_exp_f32_e32 v116, v100
	v_add_f32_e32 v6, v113, v6
	v_exp_f32_e32 v117, v101
	v_add_f32_e32 v6, v114, v6
	v_exp_f32_e32 v118, v102
	v_add_f32_e32 v6, v115, v6
	v_exp_f32_e32 v119, v103
	v_add_f32_e32 v6, v116, v6
	v_exp_f32_e32 v120, v104
	v_add_f32_e32 v6, v117, v6
	v_exp_f32_e32 v121, v105
	v_add_f32_e32 v6, v118, v6
	v_exp_f32_e32 v122, v106
	v_add_f32_e32 v6, v119, v6
	v_exp_f32_e32 v123, v107
	v_add_f32_e32 v6, v120, v6
	v_exp_f32_e32 v124, v108
	v_add_f32_e32 v6, v121, v6
	v_exp_f32_e32 v125, v109
	v_add_f32_e32 v6, v122, v6
	v_exp_f32_e32 v126, v110
	v_add_f32_e32 v6, v123, v6
	v_exp_f32_e32 v127, v111
	v_add_f32_e32 v6, v124, v6
	v_add_f32_e32 v6, v125, v6
	v_add_f32_e32 v6, v126, v6
	v_add_f32_e32 v6, v127, v6
	v_cmp_ngt_f32_e32 vcc, s25, v6
	s_cbranch_vccz .LBB0_1374
	ds_read_b128 v[190:193], v4
	ds_read_b128 v[186:189], v5
	ds_read_b128 v[182:185], v3
	ds_read_b128 v[8:11], v2
	s_waitcnt lgkmcnt(3)
	v_mfma_f32_32x32x16_bf16 v[96:111], v[190:193], v[132:135], 0
	s_waitcnt lgkmcnt(2)
	v_mfma_f32_32x32x16_bf16 v[96:111], v[186:189], v[128:131], v[96:111]
	s_waitcnt lgkmcnt(1)
	v_mfma_f32_32x32x16_bf16 v[96:111], v[182:185], v[136:139], v[96:111]
	s_waitcnt lgkmcnt(0)
	v_mfma_f32_32x32x16_bf16 v[96:111], v[8:11], v[140:143], v[96:111]
	s_branch .LBB0_1375

; #define MFMA(a, b, c) __builtin_amdgcn_mfma_f32_32x32x16_bf16((a), (b), (c), 0, 0, 0)
; DI unsigned pack2(float a, float b) { f2_t v = {a, b}; bf2_t r = __builtin_convertvector(v, bf2_t); return __builtin_bit_cast(unsigned, r); }
;     ...
;                     if ((QS == 1 || DQK == 96 || Pol::FASTEXP) && mode == 1 && __all(seen[qs] && (m[qs] == 0.f))) {
;                         float ps = 0.f;
; #pragma unroll
;                         for (int r = 0; r < 16; ++r) {
;                             const float pv = __builtin_amdgcn_exp2f(st[qs][r]);
;                             st[qs][r] = pv;
;                             ps += pv;
;                         }
;                         if (!__any(!(ps < 1048576.f))) {
;                             l[qs] += ps;
;                             exact = false;
;                         } else {
;                             asm volatile("" ::: "memory");
;                             zero_acc(st[qs]);
; #pragma unroll
;                             for (int s = 0; s < DQK / 16; ++s) {
;                                 bf16x8 kf;
;                                 if (DQK == 64) kf = *(const bf16x8*)(sK + sub * 4096 + (klane ^ (s << 5)));
;                                 else kf = *(const bf16x8*)(sK + sub * 6144 + klane + s * 32 + (s == 4 ? wrap4 : s == 5 ? wrap5 : 0));
;                                 st[qs] = MFMA(kf, qf[qs][s], st[qs]);
;                             }
;                         }
;     ...
;                     for (int s2 = 0; s2 < 2; ++s2) {
;                         union { unsigned u[4]; bf16x8 v; } pk;
; #pragma unroll
;                         for (int q = 0; q < 4; ++q) pk.u[q] = pack2(st[qs][8 * s2 + 2 * q], st[qs][8 * s2 + 2 * q + 1]);
; #pragma unroll
;                         for (int t = 0; t < DV / 32; ++t) {
;                             const bf16x8 vf = *(const bf16x8*)(sV + t * 4096 + (vlane ^ ((4 * sub + 2 * s2) << 4)));
;                             o[qs][t] = MFMA(vf, pk.v, o[qs][t]);
;                         }
;                     }
.LBB0_1390:
	s_or_b64 exec, exec, s[44:45]
	ds_read_b128 v[12:15], v4 offset:8192
	v_cvt_pk_bf16_f32 v8, v112, v113
	v_cvt_pk_bf16_f32 v9, v114, v115
	v_cvt_pk_bf16_f32 v10, v116, v117
	v_cvt_pk_bf16_f32 v11, v118, v119
	s_mov_b64 s[44:45], s[42:43]
	s_waitcnt lgkmcnt(0)
	v_mfma_f32_32x32x16_bf16 v[64:79], v[12:15], v[8:11], v[64:79]
	ds_read_b128 v[186:189], v4 offset:12288
	ds_read_b128 v[182:185], v4 offset:16384
	ds_read_b128 v[12:15], v4 offset:20480
	s_waitcnt lgkmcnt(2)
	v_mfma_f32_32x32x16_bf16 v[48:63], v[186:189], v[8:11], v[48:63]
	s_waitcnt lgkmcnt(1)
	v_mfma_f32_32x32x16_bf16 v[32:47], v[182:185], v[8:11], v[32:47]
	s_waitcnt lgkmcnt(0)
	v_mfma_f32_32x32x16_bf16 v[16:31], v[12:15], v[8:11], v[16:31]
	ds_read_b128 v[12:15], v5 offset:8192
	v_cvt_pk_bf16_f32 v8, v120, v121
	v_cvt_pk_bf16_f32 v9, v122, v123
	v_cvt_pk_bf16_f32 v10, v124, v125
	v_cvt_pk_bf16_f32 v11, v126, v127
	s_waitcnt lgkmcnt(0)
	s_nop 0
	v_mfma_f32_32x32x16_bf16 v[64:79], v[12:15], v[8:11], v[64:79]
	ds_read_b128 v[186:189], v5 offset:12288
	ds_read_b128 v[182:185], v5 offset:16384
	ds_read_b128 v[12:15], v5 offset:20480
	s_waitcnt lgkmcnt(2)
	v_mfma_f32_32x32x16_bf16 v[48:63], v[186:189], v[8:11], v[48:63]
	s_waitcnt lgkmcnt(1)
	v_mfma_f32_32x32x16_bf16 v[32:47], v[182:185], v[8:11], v[32:47]
	s_waitcnt lgkmcnt(0)
	v_mfma_f32_32x32x16_bf16 v[16:31], v[12:15], v[8:11], v[16:31]
	s_and_saveexec_b64 s[36:37], s[0:1]
	s_cbranch_execz .LBB0_1397
	v_cmp_eq_f32_e32 vcc, 0, v174
	s_and_b64 s[0:1], s[16:17], vcc
	v_cndmask_b32_e64 v7, 0, 1, s[0:1]
	v_cmp_ne_u32_e32 vcc, 0, v7
	s_cmp_eq_u64 vcc, exec
	s_mov_b64 s[0:1], -1
	s_cbranch_scc0 .LBB0_1394
	v_exp_f32_e32 v96, v80
	v_exp_f32_e32 v97, v81
	v_exp_f32_e32 v98, v82
	v_exp_f32_e32 v99, v83
	v_add_f32_e32 v7, 0, v96
	v_exp_f32_e32 v100, v84
	v_add_f32_e32 v7, v97, v7
	v_exp_f32_e32 v101, v85
	v_add_f32_e32 v7, v98, v7
	v_exp_f32_e32 v102, v86
	v_add_f32_e32 v7, v99, v7
	v_exp_f32_e32 v103, v87
	v_add_f32_e32 v7, v100, v7
	v_exp_f32_e32 v104, v88
	v_add_f32_e32 v7, v101, v7
	v_exp_f32_e32 v105, v89
	v_add_f32_e32 v7, v102, v7
	v_exp_f32_e32 v106, v90
	v_add_f32_e32 v7, v103, v7
	v_exp_f32_e32 v107, v91
	v_add_f32_e32 v7, v104, v7
	v_exp_f32_e32 v108, v92
	v_add_f32_e32 v7, v105, v7
	v_exp_f32_e32 v109, v93
	v_add_f32_e32 v7, v106, v7
	v_exp_f32_e32 v110, v94
	v_add_f32_e32 v7, v107, v7
	v_exp_f32_e32 v111, v95
	v_add_f32_e32 v7, v108, v7
	v_add_f32_e32 v7, v109, v7
	v_add_f32_e32 v7, v110, v7
	v_add_f32_e32 v7, v111, v7
	v_cmp_ngt_f32_e32 vcc, s25, v7
	s_cbranch_vccz .LBB0_1395
	ds_read_b128 v[190:193], v4 offset:4096
	ds_read_b128 v[186:189], v5 offset:4096
	ds_read_b128 v[182:185], v3 offset:4096
	ds_read_b128 v[8:11], v2 offset:4096
	s_waitcnt lgkmcnt(3)
	v_mfma_f32_32x32x16_bf16 v[80:95], v[190:193], v[132:135], 0
	s_waitcnt lgkmcnt(2)
	v_mfma_f32_32x32x16_bf16 v[80:95], v[186:189], v[128:131], v[80:95]
	s_waitcnt lgkmcnt(1)
	v_mfma_f32_32x32x16_bf16 v[80:95], v[182:185], v[136:139], v[80:95]
	s_waitcnt lgkmcnt(0)
	v_mfma_f32_32x32x16_bf16 v[80:95], v[8:11], v[140:143], v[80:95]
	s_branch .LBB0_1396

; #define MFMA(a, b, c) __builtin_amdgcn_mfma_f32_32x32x16_bf16((a), (b), (c), 0, 0, 0)
; DI unsigned pack2(float a, float b) { f2_t v = {a, b}; bf2_t r = __builtin_convertvector(v, bf2_t); return __builtin_bit_cast(unsigned, r); }
;     ...
;                     for (int s2 = 0; s2 < 2; ++s2) {
;                         union { unsigned u[4]; bf16x8 v; } pk;
; #pragma unroll
;                         for (int q = 0; q < 4; ++q) pk.u[q] = pack2(st[qs][8 * s2 + 2 * q], st[qs][8 * s2 + 2 * q + 1]);
; #pragma unroll
;                         for (int t = 0; t < DV / 32; ++t) {
;                             const bf16x8 vf = *(const bf16x8*)(sV + t * 4096 + (vlane ^ ((4 * sub + 2 * s2) << 4)));
;                             o[qs][t] = MFMA(vf, pk.v, o[qs][t]);
;                         }
;                     }
.LBB0_1411:
	s_or_b64 exec, exec, s[36:37]
	ds_read_b128 v[8:11], v3 offset:8192
	v_add_f32_e32 v0, v0, v7
	v_cvt_pk_bf16_f32 v4, v96, v97
	v_cvt_pk_bf16_f32 v5, v98, v99
	v_cvt_pk_bf16_f32 v6, v100, v101
	v_cvt_pk_bf16_f32 v7, v102, v103
	s_andn2_b64 s[0:1], s[12:13], exec
	s_and_b64 s[12:13], s[16:17], exec
	s_or_b64 s[12:13], s[0:1], s[12:13]
	s_waitcnt lgkmcnt(0)
	v_mfma_f32_32x32x16_bf16 v[64:79], v[8:11], v[4:7], v[64:79]
	ds_read_b128 v[186:189], v3 offset:12288
	ds_read_b128 v[182:185], v3 offset:16384
	ds_read_b128 v[8:11], v3 offset:20480
	s_waitcnt lgkmcnt(2)
	v_mfma_f32_32x32x16_bf16 v[48:63], v[186:189], v[4:7], v[48:63]
	s_waitcnt lgkmcnt(1)
	v_mfma_f32_32x32x16_bf16 v[32:47], v[182:185], v[4:7], v[32:47]
	s_waitcnt lgkmcnt(0)
	v_mfma_f32_32x32x16_bf16 v[16:31], v[8:11], v[4:7], v[16:31]
	ds_read_b128 v[8:11], v2 offset:8192
	v_cvt_pk_bf16_f32 v4, v104, v105
	v_cvt_pk_bf16_f32 v5, v106, v107
	v_cvt_pk_bf16_f32 v6, v108, v109
	v_cvt_pk_bf16_f32 v7, v110, v111
	s_waitcnt lgkmcnt(0)
	s_nop 0
	v_mfma_f32_32x32x16_bf16 v[64:79], v[8:11], v[4:7], v[64:79]
	ds_read_b128 v[186:189], v2 offset:12288
	ds_read_b128 v[182:185], v2 offset:16384
	ds_read_b128 v[8:11], v2 offset:20480
	s_waitcnt lgkmcnt(2)
	v_mfma_f32_32x32x16_bf16 v[48:63], v[186:189], v[4:7], v[48:63]
	s_waitcnt lgkmcnt(1)
	v_mfma_f32_32x32x16_bf16 v[32:47], v[182:185], v[4:7], v[32:47]
	s_waitcnt lgkmcnt(0)
	v_mfma_f32_32x32x16_bf16 v[16:31], v[8:11], v[4:7], v[16:31]

; #define MFMA(a, b, c) __builtin_amdgcn_mfma_f32_32x32x16_bf16((a), (b), (c), 0, 0, 0)
;     ...
;     while (kt0 < kt_hi) {
;         if (kt1 < kt_hi) asm volatile("s_waitcnt vmcnt(%0)" ::"n"(NI) : "memory");
;         else asm volatile("s_waitcnt vmcnt(0)" ::: "memory");
;         RAW_BARRIER();
;         int kt2 = kt1 + 1;
;         while (kt2 < kt_hi && pol.bskip(kt2)) ++kt2;
;         if (kt2 < kt_hi) issue(kt2, b >= 1 ? b - 1 : 2);
;         const char* sK = smem + b * STAGE;
;         const char* sV = sK + KBYTES;
;         const int kt = kt0;
;         const int mode = pol.wmode(kt);
;         if (mode) {
;             auto qk = [&](const int sub, f32x16 (&st)[QS]) {
; #pragma unroll
;                 for (int qs = 0; qs < QS; ++qs) zero_acc(st[qs]);
; #pragma unroll
;                 for (int s = 0; s < DQK / 16; ++s) {
;                     bf16x8 kf;
;                     if (DQK == 64) kf = *(const bf16x8*)(sK + sub * 4096 + (klane ^ (s << 5)));
;                     else kf = *(const bf16x8*)(sK + sub * 6144 + klane + s * 32 + (s == 4 ? wrap4 : s == 5 ? wrap5 : 0));
; #pragma unroll
;                     for (int qs = 0; qs < QS; ++qs) st[qs] = MFMA(kf, qf[qs][s], st[qs]);
;                 }
;             };
;             auto sm_pv = [&](const int sub, f32x16 (&st)[QS]) {
; #pragma unroll
;                 for (int qs = 0; qs < QS; ++qs) {
;                     bool exact = true;
;                     if ((QS == 1 || DQK == 96 || Pol::FASTEXP) && mode == 1 && __all(seen[qs] && (m[qs] == 0.f))) {
;                         float ps = 0.f;
; #pragma unroll
;                         for (int r = 0; r < 16; ++r) {
;                             const float pv = __builtin_amdgcn_exp2f(st[qs][r]);
;                             st[qs][r] = pv;
;                             ps += pv;
;                         }
;                         if (!__any(!(ps < 1048576.f))) {
;                             l[qs] += ps;
;                             exact = false;
;                         } else {
;                             asm volatile("" ::: "memory");
;                             zero_acc(st[qs]);
; #pragma unroll
;                             for (int s = 0; s < DQK / 16; ++s) {
;                                 bf16x8 kf;
;                                 if (DQK == 64) kf = *(const bf16x8*)(sK + sub * 4096 + (klane ^ (s << 5)));
.LBB0_1414:
	s_waitcnt vmcnt(0)
	s_waitcnt lgkmcnt(0)
	s_lshl_b32 s45, s75, 6
	v_cmp_le_i32_e32 vcc, s45, v168
	s_barrier
	s_and_saveexec_b64 s[14:15], vcc
	s_cbranch_execz .LBB0_1458
	s_mul_i32 s44, s62, 0x6000
	v_or_b32_e32 v6, s44, v173
	s_waitcnt vmcnt(0)
	ds_read_b128 v[2:5], v6
	v_or_b32_e32 v7, s44, v172
	v_or_b32_e32 v8, s44, v170
	v_or_b32_e32 v9, s44, v169
	s_or_b32 s0, s45, 63
	v_cmp_gt_i32_e64 s[16:17], s0, v168
	v_cmp_le_i32_e64 s[0:1], s0, v168
	s_mov_b64 s[42:43], s[16:17]
	s_waitcnt lgkmcnt(0)
	v_mfma_f32_32x32x16_bf16 v[96:111], v[2:5], v[132:135], 0
	ds_read_b128 v[186:189], v7
	ds_read_b128 v[182:185], v8
	ds_read_b128 v[2:5], v9
	ds_read_b128 v[190:193], v6 offset:4096
	s_waitcnt lgkmcnt(3)
	v_mfma_f32_32x32x16_bf16 v[96:111], v[186:189], v[128:131], v[96:111]
	ds_read_b128 v[186:189], v7 offset:4096
	s_waitcnt lgkmcnt(3)
	v_mfma_f32_32x32x16_bf16 v[96:111], v[182:185], v[136:139], v[96:111]
	ds_read_b128 v[182:185], v8 offset:4096
	s_waitcnt lgkmcnt(3)
	v_mfma_f32_32x32x16_bf16 v[96:111], v[2:5], v[140:143], v[96:111]
	ds_read_b128 v[2:5], v9 offset:4096
	s_waitcnt lgkmcnt(3)
	v_mfma_f32_32x32x16_bf16 v[80:95], v[190:193], v[132:135], 0
	s_waitcnt lgkmcnt(2)
	v_mfma_f32_32x32x16_bf16 v[80:95], v[186:189], v[128:131], v[80:95]
	s_waitcnt lgkmcnt(1)
	v_mfma_f32_32x32x16_bf16 v[80:95], v[182:185], v[136:139], v[80:95]
	s_waitcnt lgkmcnt(0)
	v_mfma_f32_32x32x16_bf16 v[80:95], v[2:5], v[140:143], v[80:95]
	s_and_saveexec_b64 s[36:37], s[0:1]
	s_cbranch_execz .LBB0_1422
	v_cmp_eq_f32_e32 vcc, 0, v174
	s_and_b64 s[18:19], s[12:13], vcc
	v_cndmask_b32_e64 v2, 0, 1, s[18:19]
	v_cmp_ne_u32_e32 vcc, 0, v2
	s_cmp_eq_u64 vcc, exec
	s_mov_b64 s[38:39], -1
	s_cbranch_scc0 .LBB0_1419
	v_exp_f32_e32 v112, v96
	v_exp_f32_e32 v113, v97
	v_exp_f32_e32 v114, v98
	v_exp_f32_e32 v115, v99
	v_add_f32_e32 v2, 0, v112
	v_exp_f32_e32 v116, v100
	v_add_f32_e32 v2, v113, v2
	v_exp_f32_e32 v117, v101
	v_add_f32_e32 v2, v114, v2
	v_exp_f32_e32 v118, v102
	v_add_f32_e32 v2, v115, v2
	v_exp_f32_e32 v119, v103
	v_add_f32_e32 v2, v116, v2
	v_exp_f32_e32 v120, v104
	v_add_f32_e32 v2, v117, v2
	v_exp_f32_e32 v121, v105
	v_add_f32_e32 v2, v118, v2
	v_exp_f32_e32 v122, v106
	v_add_f32_e32 v2, v119, v2
	v_exp_f32_e32 v123, v107
	v_add_f32_e32 v2, v120, v2
	v_exp_f32_e32 v124, v108
	v_add_f32_e32 v2, v121, v2
	v_exp_f32_e32 v125, v109
	v_add_f32_e32 v2, v122, v2
	v_exp_f32_e32 v126, v110
	v_add_f32_e32 v2, v123, v2
	v_exp_f32_e32 v127, v111
	v_add_f32_e32 v2, v124, v2
	v_add_f32_e32 v2, v125, v2
	v_add_f32_e32 v2, v126, v2
	v_add_f32_e32 v2, v127, v2
	v_cmp_ngt_f32_e32 vcc, s25, v2
	s_cbranch_vccz .LBB0_1420
	v_add_u32_e32 v3, s44, v173
	ds_read_b128 v[4:7], v3
	v_add_u32_e32 v3, s44, v172
	s_waitcnt lgkmcnt(0)
	v_mfma_f32_32x32x16_bf16 v[96:111], v[4:7], v[132:135], 0
	ds_read_b128 v[4:7], v3
	v_add_u32_e32 v3, s44, v170
	s_waitcnt lgkmcnt(0)
	v_mfma_f32_32x32x16_bf16 v[96:111], v[4:7], v[128:131], v[96:111]
	ds_read_b128 v[4:7], v3
	v_add_u32_e32 v3, s44, v169
	s_waitcnt lgkmcnt(0)
	v_mfma_f32_32x32x16_bf16 v[96:111], v[4:7], v[136:139], v[96:111]
	ds_read_b128 v[4:7], v3
	s_waitcnt lgkmcnt(0)
	v_mfma_f32_32x32x16_bf16 v[96:111], v[4:7], v[140:143], v[96:111]
	s_branch .LBB0_1421

; #define MFMA(a, b, c) __builtin_amdgcn_mfma_f32_32x32x16_bf16((a), (b), (c), 0, 0, 0)
; DI unsigned pack2(float a, float b) { f2_t v = {a, b}; bf2_t r = __builtin_convertvector(v, bf2_t); return __builtin_bit_cast(unsigned, r); }
;     ...
;                     if ((QS == 1 || DQK == 96 || Pol::FASTEXP) && mode == 1 && __all(seen[qs] && (m[qs] == 0.f))) {
;                         float ps = 0.f;
; #pragma unroll
;                         for (int r = 0; r < 16; ++r) {
;                             const float pv = __builtin_amdgcn_exp2f(st[qs][r]);
;                             st[qs][r] = pv;
;                             ps += pv;
;                         }
;                         if (!__any(!(ps < 1048576.f))) {
;                             l[qs] += ps;
;                             exact = false;
;                         } else {
;                             asm volatile("" ::: "memory");
;                             zero_acc(st[qs]);
; #pragma unroll
;                             for (int s = 0; s < DQK / 16; ++s) {
;                                 bf16x8 kf;
;                                 if (DQK == 64) kf = *(const bf16x8*)(sK + sub * 4096 + (klane ^ (s << 5)));
;                                 else kf = *(const bf16x8*)(sK + sub * 6144 + klane + s * 32 + (s == 4 ? wrap4 : s == 5 ? wrap5 : 0));
;                                 st[qs] = MFMA(kf, qf[qs][s], st[qs]);
;                             }
;                         }
;     ...
;                     for (int s2 = 0; s2 < 2; ++s2) {
;                         union { unsigned u[4]; bf16x8 v; } pk;
; #pragma unroll
;                         for (int q = 0; q < 4; ++q) pk.u[q] = pack2(st[qs][8 * s2 + 2 * q], st[qs][8 * s2 + 2 * q + 1]);
; #pragma unroll
;                         for (int t = 0; t < DV / 32; ++t) {
;                             const bf16x8 vf = *(const bf16x8*)(sV + t * 4096 + (vlane ^ ((4 * sub + 2 * s2) << 4)));
;                             o[qs][t] = MFMA(vf, pk.v, o[qs][t]);
;                         }
;                     }
.LBB0_1436:
	s_or_b64 exec, exec, s[38:39]
	v_add_u32_e32 v3, s44, v173
	ds_read_b128 v[8:11], v3 offset:8192
	v_cvt_pk_bf16_f32 v4, v112, v113
	v_cvt_pk_bf16_f32 v5, v114, v115
	v_cvt_pk_bf16_f32 v6, v116, v117
	v_cvt_pk_bf16_f32 v7, v118, v119
	s_mov_b64 s[38:39], s[16:17]
	s_waitcnt lgkmcnt(0)
	v_mfma_f32_32x32x16_bf16 v[64:79], v[8:11], v[4:7], v[64:79]
	ds_read_b128 v[186:189], v3 offset:12288
	ds_read_b128 v[182:185], v3 offset:16384
	ds_read_b128 v[8:11], v3 offset:20480
	s_waitcnt lgkmcnt(2)
	v_mfma_f32_32x32x16_bf16 v[48:63], v[186:189], v[4:7], v[48:63]
	s_waitcnt lgkmcnt(1)
	v_mfma_f32_32x32x16_bf16 v[32:47], v[182:185], v[4:7], v[32:47]
	s_waitcnt lgkmcnt(0)
	v_mfma_f32_32x32x16_bf16 v[16:31], v[8:11], v[4:7], v[16:31]
	v_add_u32_e32 v5, s44, v172
	ds_read_b128 v[10:13], v5 offset:8192
	v_cvt_pk_bf16_f32 v6, v120, v121
	v_cvt_pk_bf16_f32 v7, v122, v123
	v_cvt_pk_bf16_f32 v8, v124, v125
	v_cvt_pk_bf16_f32 v9, v126, v127
	s_waitcnt lgkmcnt(0)
	s_nop 0
	v_mfma_f32_32x32x16_bf16 v[64:79], v[10:13], v[6:9], v[64:79]
	ds_read_b128 v[186:189], v5 offset:12288
	ds_read_b128 v[182:185], v5 offset:16384
	ds_read_b128 v[10:13], v5 offset:20480
	s_waitcnt lgkmcnt(2)
	v_mfma_f32_32x32x16_bf16 v[48:63], v[186:189], v[6:9], v[48:63]
	s_waitcnt lgkmcnt(1)
	v_mfma_f32_32x32x16_bf16 v[32:47], v[182:185], v[6:9], v[32:47]
	s_waitcnt lgkmcnt(0)
	v_mfma_f32_32x32x16_bf16 v[16:31], v[10:13], v[6:9], v[16:31]
	s_and_saveexec_b64 s[36:37], s[0:1]
	s_cbranch_execz .LBB0_1443
	v_cmp_eq_f32_e32 vcc, 0, v174
	s_and_b64 s[0:1], s[12:13], vcc
	v_cndmask_b32_e64 v4, 0, 1, s[0:1]
	v_cmp_ne_u32_e32 vcc, 0, v4
	s_cmp_eq_u64 vcc, exec
	s_mov_b64 s[0:1], -1
	s_cbranch_scc0 .LBB0_1440
	v_exp_f32_e32 v96, v80
	v_exp_f32_e32 v97, v81
	v_exp_f32_e32 v98, v82
	v_exp_f32_e32 v99, v83
	v_add_f32_e32 v4, 0, v96
	v_exp_f32_e32 v100, v84
	v_add_f32_e32 v4, v97, v4
	v_exp_f32_e32 v101, v85
	v_add_f32_e32 v4, v98, v4
	v_exp_f32_e32 v102, v86
	v_add_f32_e32 v4, v99, v4
	v_exp_f32_e32 v103, v87
	v_add_f32_e32 v4, v100, v4
	v_exp_f32_e32 v104, v88
	v_add_f32_e32 v4, v101, v4
	v_exp_f32_e32 v105, v89
	v_add_f32_e32 v4, v102, v4
	v_exp_f32_e32 v106, v90
	v_add_f32_e32 v4, v103, v4
	v_exp_f32_e32 v107, v91
	v_add_f32_e32 v4, v104, v4
	v_exp_f32_e32 v108, v92
	v_add_f32_e32 v4, v105, v4
	v_exp_f32_e32 v109, v93
	v_add_f32_e32 v4, v106, v4
	v_exp_f32_e32 v110, v94
	v_add_f32_e32 v4, v107, v4
	v_exp_f32_e32 v111, v95
	v_add_f32_e32 v4, v108, v4
	v_add_f32_e32 v4, v109, v4
	v_add_f32_e32 v4, v110, v4
	v_add_f32_e32 v4, v111, v4
	v_cmp_ngt_f32_e32 vcc, s25, v4
	s_cbranch_vccz .LBB0_1441
	ds_read_b128 v[6:9], v3 offset:4096
	v_add_u32_e32 v3, s44, v170
	s_waitcnt lgkmcnt(0)
	v_mfma_f32_32x32x16_bf16 v[80:95], v[6:9], v[132:135], 0
	ds_read_b128 v[6:9], v5 offset:4096
	s_waitcnt lgkmcnt(0)
	v_mfma_f32_32x32x16_bf16 v[80:95], v[6:9], v[128:131], v[80:95]
	ds_read_b128 v[6:9], v3 offset:4096
	v_add_u32_e32 v3, s44, v169
	s_waitcnt lgkmcnt(0)
	v_mfma_f32_32x32x16_bf16 v[80:95], v[6:9], v[136:139], v[80:95]
	ds_read_b128 v[6:9], v3 offset:4096
	s_waitcnt lgkmcnt(0)
	v_mfma_f32_32x32x16_bf16 v[80:95], v[6:9], v[140:143], v[80:95]
	s_branch .LBB0_1442

; #define MFMA(a, b, c) __builtin_amdgcn_mfma_f32_32x32x16_bf16((a), (b), (c), 0, 0, 0)
; DI unsigned pack2(float a, float b) { f2_t v = {a, b}; bf2_t r = __builtin_convertvector(v, bf2_t); return __builtin_bit_cast(unsigned, r); }
;     ...
;                     for (int s2 = 0; s2 < 2; ++s2) {
;                         union { unsigned u[4]; bf16x8 v; } pk;
; #pragma unroll
;                         for (int q = 0; q < 4; ++q) pk.u[q] = pack2(st[qs][8 * s2 + 2 * q], st[qs][8 * s2 + 2 * q + 1]);
; #pragma unroll
;                         for (int t = 0; t < DV / 32; ++t) {
;                             const bf16x8 vf = *(const bf16x8*)(sV + t * 4096 + (vlane ^ ((4 * sub + 2 * s2) << 4)));
;                             o[qs][t] = MFMA(vf, pk.v, o[qs][t]);
;                         }
;                     }
.LBB0_1457:
	s_or_b64 exec, exec, s[0:1]
	v_add_u32_e32 v10, s44, v170
	ds_read_b128 v[6:9], v10 offset:8192
	v_add_f32_e32 v0, v0, v4
	v_cvt_pk_bf16_f32 v2, v96, v97
	v_cvt_pk_bf16_f32 v3, v98, v99
	v_cvt_pk_bf16_f32 v4, v100, v101
	v_cvt_pk_bf16_f32 v5, v102, v103
	s_waitcnt lgkmcnt(0)
	s_nop 0
	v_mfma_f32_32x32x16_bf16 v[64:79], v[6:9], v[2:5], v[64:79]
	ds_read_b128 v[6:9], v10 offset:12288
	s_waitcnt lgkmcnt(0)
	v_mfma_f32_32x32x16_bf16 v[48:63], v[6:9], v[2:5], v[48:63]
	ds_read_b128 v[6:9], v10 offset:16384
	s_waitcnt lgkmcnt(0)
	v_mfma_f32_32x32x16_bf16 v[32:47], v[6:9], v[2:5], v[32:47]
	ds_read_b128 v[6:9], v10 offset:20480
	v_add_u32_e32 v10, s44, v169
	s_waitcnt lgkmcnt(0)
	v_mfma_f32_32x32x16_bf16 v[16:31], v[6:9], v[2:5], v[16:31]
	ds_read_b128 v[6:9], v10 offset:8192
	v_cvt_pk_bf16_f32 v2, v104, v105
	v_cvt_pk_bf16_f32 v3, v106, v107
	v_cvt_pk_bf16_f32 v4, v108, v109
	v_cvt_pk_bf16_f32 v5, v110, v111
	s_waitcnt lgkmcnt(0)
	s_nop 0
	v_mfma_f32_32x32x16_bf16 v[64:79], v[6:9], v[2:5], v[64:79]
	ds_read_b128 v[186:189], v10 offset:12288
	ds_read_b128 v[182:185], v10 offset:16384
	ds_read_b128 v[6:9], v10 offset:20480
	s_waitcnt lgkmcnt(2)
	v_mfma_f32_32x32x16_bf16 v[48:63], v[186:189], v[2:5], v[48:63]
	s_waitcnt lgkmcnt(1)
	v_mfma_f32_32x32x16_bf16 v[32:47], v[182:185], v[2:5], v[32:47]
	s_waitcnt lgkmcnt(0)
	v_mfma_f32_32x32x16_bf16 v[16:31], v[6:9], v[2:5], v[16:31]

; #define MFMA(a, b, c) __builtin_amdgcn_mfma_f32_32x32x16_bf16((a), (b), (c), 0, 0, 0)
; template <bool SWAP, int MI>
; DI void gemm_main(const bf16_t* __restrict__ A, int lda, const bf16_t* __restrict__ B, int ldb, int K, char* smem, f32x16 (&acc)[MI][2]) {
;     ...
;     const int lr = tid >> 3, lc = (tid & 7) * 8;
;     const bf16_t* ap = A + (size_t)lr * lda + lc;
;     const bf16_t* bp = B + (size_t)lr * ldb + lc;
; #pragma unroll
;     for (int i = 0; i < 2 * MI; ++i) ra[i] = *(const u32x4*)(ap + (size_t)(32 * i) * lda);
; #pragma unroll
;     for (int i = 0; i < 4; ++i) rb[i] = *(const u32x4*)(bp + (size_t)(32 * i) * ldb);
;     __syncthreads();
; #pragma unroll
;     for (int i = 0; i < 2 * MI; ++i) *(u32x4*)(sA + (lr + 32 * i) * GLD + lc) = ra[i];
; #pragma unroll
;     for (int i = 0; i < 4; ++i) *(u32x4*)(sB + (lr + 32 * i) * GLD + lc) = rb[i];
;     __syncthreads();
;     for (int k0 = 0; k0 < K; k0 += 64) {
;         const bool more = (k0 + 64) < K;
;         if (more) {
; #pragma unroll
;             for (int i = 0; i < 2 * MI; ++i) ra[i] = *(const u32x4*)(ap + (size_t)(32 * i) * lda + k0 + 64);
; #pragma unroll
;             for (int i = 0; i < 4; ++i) rb[i] = *(const u32x4*)(bp + (size_t)(32 * i) * ldb + k0 + 64);
;         }
; #pragma unroll
;         for (int s = 0; s < 4; ++s) {
;             bf16x8 af[MI], bfr[2];
; #pragma unroll
;             for (int i = 0; i < MI; ++i) af[i] = *(const bf16x8*)(sA + (wm * (MI * 32) + i * 32 + l31) * GLD + s * 16 + h * 8);
; #pragma unroll
;             for (int j = 0; j < 2; ++j) bfr[j] = *(const bf16x8*)(sB + (wn * 64 + j * 32 + l31) * GLD + s * 16 + h * 8);
; #pragma unroll
;             for (int i = 0; i < MI; ++i)
; #pragma unroll
;                 for (int j = 0; j < 2; ++j) {
;                     if (SWAP) acc[i][j] = MFMA(bfr[j], af[i], acc[i][j]);
;                     else acc[i][j] = MFMA(af[i], bfr[j], acc[i][j]);
;                 }
;         }
;         __syncthreads();
;         if (more) {
; #pragma unroll
;             for (int i = 0; i < 2 * MI; ++i) *(u32x4*)(sA + (lr + 32 * i) * GLD + lc) = ra[i];
; #pragma unroll
;             for (int i = 0; i < 4; ++i) *(u32x4*)(sB + (lr + 32 * i) * GLD + lc) = rb[i];
;         }
;         __syncthreads();
.LBB0_1476:
	s_or_b64 exec, exec, s[0:1]
	s_and_b32 s15, s72, 7
	s_lshl_b32 s14, s15, 7
	s_lshl_b32 s0, s15, 15
	s_add_u32 s10, s21, s0
	s_mov_b32 s9, s61
	s_addc_u32 s11, s22, 0
	s_lshl_b64 s[0:1], s[8:9], 8
	v_readlane_b32 s12, v245, 7
	v_readlane_b32 s13, v245, 8
	s_add_u32 s12, s12, s0
	s_addc_u32 s13, s13, s1
	s_cmp_gt_u32 s15, 3
	s_mov_b64 s[0:1], -1
	s_cbranch_scc0 .LBB0_1494
	v_mov_b32_e32 v37, v196
	s_movk_i32 s0, 0x2000
	v_ashrrev_i32_e32 v34, 3, v37
	v_ashrrev_i32_e32 v35, 31, v34
	v_lshlrev_b64 v[2:3], 8, v[34:35]
	v_lshlrev_b32_e32 v0, 4, v37
	v_lshl_add_u64 v[4:5], s[12:13], 0, v[2:3]
	v_and_b32_e32 v0, 0x70, v0
	v_lshl_add_u64 v[104:105], v[4:5], 0, v[0:1]
	v_add_co_u32_e32 v106, vcc, 0x2000, v104
	v_lshl_add_u64 v[18:19], s[10:11], 0, v[2:3]
	s_nop 0
	v_addc_co_u32_e32 v107, vcc, 0, v105, vcc
	v_add_co_u32_e32 v108, vcc, 0x4000, v104
	v_lshl_add_u64 v[112:113], v[18:19], 0, v[0:1]
	s_nop 0
	v_addc_co_u32_e32 v109, vcc, 0, v105, vcc
	v_add_co_u32_e32 v110, vcc, 0x6000, v104
	global_load_dwordx4 v[2:5], v[104:105], off
	global_load_dwordx4 v[6:9], v[106:107], off
	v_addc_co_u32_e32 v111, vcc, 0, v105, vcc
	v_add_co_u32_e32 v114, vcc, s0, v112
	s_movk_i32 s0, 0x6000
	s_nop 0
	v_addc_co_u32_e32 v115, vcc, 0, v113, vcc
	v_add_co_u32_e32 v116, vcc, s52, v112
	global_load_dwordx4 v[10:13], v[108:109], off
	global_load_dwordx4 v[14:17], v[110:111], off
	v_addc_co_u32_e32 v117, vcc, 0, v113, vcc
	v_add_co_u32_e32 v118, vcc, s0, v112
	global_load_dwordx4 v[18:21], v[112:113], off
	global_load_dwordx4 v[22:25], v[114:115], off
	v_addc_co_u32_e32 v119, vcc, 0, v113, vcc
	global_load_dwordx4 v[26:29], v[116:117], off
	global_load_dwordx4 v[30:33], v[118:119], off
	v_and_b32_e32 v35, 31, v37
	v_lshrrev_b32_e32 v36, 1, v37
	s_mov_b32 s0, 0xfffffc0
	v_and_or_b32 v35, v36, s0, v35
	v_and_b32_e32 v36, 16, v36
	v_mad_u64_u32 v[120:121], s[0:1], v34, s35, v[0:1]
	v_mad_u64_u32 v[122:123], s[0:1], v35, s35, v[36:37]
	s_waitcnt lgkmcnt(0)
	s_barrier
	v_and_b32_e32 v0, 0x5f, v37
	v_mad_u32_u24 v0, v0, s35, v36
	s_mov_b64 s[16:17], -1
	s_andn2_b64 vcc, exec, s[16:17]
	s_waitcnt vmcnt(7)
	ds_write_b128 v120, v[2:5]
	s_waitcnt vmcnt(3)
	ds_write_b128 v120, v[18:21] offset:18432
	ds_write_b128 v120, v[6:9] offset:4608
	ds_write_b128 v120, v[10:13] offset:9216
	ds_write_b128 v120, v[14:17] offset:13824
	s_waitcnt vmcnt(2)
	ds_write_b128 v120, v[22:25] offset:23040
	s_waitcnt vmcnt(1)
	ds_write_b128 v120, v[26:29] offset:27648
	s_waitcnt vmcnt(0)
	ds_write_b128 v120, v[30:33] offset:32256
	s_waitcnt lgkmcnt(0)
	s_barrier
	ds_read_b128 v[2:5], v122
	ds_read_b128 v[6:9], v0 offset:18432
	ds_read_b128 v[72:75], v122 offset:32
	ds_read_b128 v[76:79], v0 offset:18464
	ds_read_b128 v[10:13], v0 offset:23040
	ds_read_b128 v[80:83], v0 offset:23072
	s_waitcnt lgkmcnt(4)
	v_mfma_f32_32x32x16_bf16 v[50:65], v[2:5], v[6:9], 0
	s_waitcnt lgkmcnt(1)
	v_mfma_f32_32x32x16_bf16 v[18:33], v[2:5], v[10:13], 0
	ds_read_b128 v[2:5], v122 offset:4608
	ds_read_b128 v[84:87], v122 offset:4640
	s_waitcnt lgkmcnt(1)
	v_mfma_f32_32x32x16_bf16 v[34:49], v[2:5], v[6:9], 0
	v_mfma_f32_32x32x16_bf16 v[2:17], v[2:5], v[10:13], 0
	v_mfma_f32_32x32x16_bf16 v[50:65], v[72:75], v[76:79], v[50:65]
	v_mfma_f32_32x32x16_bf16 v[18:33], v[72:75], v[80:83], v[18:33]
	s_waitcnt lgkmcnt(0)
	v_mfma_f32_32x32x16_bf16 v[34:49], v[84:87], v[76:79], v[34:49]
	v_mfma_f32_32x32x16_bf16 v[2:17], v[84:87], v[80:83], v[2:17]
	ds_read_b128 v[72:75], v122 offset:64
	ds_read_b128 v[76:79], v0 offset:18496
	ds_read_b128 v[80:83], v122 offset:96
	ds_read_b128 v[84:87], v0 offset:18528
	ds_read_b128 v[88:91], v0 offset:23104
	ds_read_b128 v[96:99], v0 offset:23136
	s_waitcnt lgkmcnt(4)
	v_mfma_f32_32x32x16_bf16 v[50:65], v[72:75], v[76:79], v[50:65]
	s_waitcnt lgkmcnt(1)
	v_mfma_f32_32x32x16_bf16 v[18:33], v[72:75], v[88:91], v[18:33]
	ds_read_b128 v[72:75], v122 offset:4672
	ds_read_b128 v[100:103], v122 offset:4704
	s_waitcnt lgkmcnt(1)
	v_mfma_f32_32x32x16_bf16 v[34:49], v[72:75], v[76:79], v[34:49]
	v_mfma_f32_32x32x16_bf16 v[2:17], v[72:75], v[88:91], v[2:17]
	v_mfma_f32_32x32x16_bf16 v[50:65], v[80:83], v[84:87], v[50:65]
	v_mfma_f32_32x32x16_bf16 v[18:33], v[80:83], v[96:99], v[18:33]
	global_load_dwordx4 v[72:75], v[104:105], off offset:128
	global_load_dwordx4 v[76:79], v[106:107], off offset:128
	global_load_dwordx4 v[80:83], v[108:109], off offset:128
	global_load_dwordx4 v[88:91], v[110:111], off offset:128
	s_nop 0
	global_load_dwordx4 v[104:107], v[112:113], off offset:128
	global_load_dwordx4 v[108:111], v[114:115], off offset:128
	s_waitcnt lgkmcnt(0)
	v_mfma_f32_32x32x16_bf16 v[34:49], v[100:103], v[84:87], v[34:49]
	global_load_dwordx4 v[84:87], v[116:117], off offset:128
	global_load_dwordx4 v[112:115], v[118:119], off offset:128
	s_barrier
; #define MFMA(a, b, c) __builtin_amdgcn_mfma_f32_32x32x16_bf16((a), (b), (c), 0, 0, 0)
; template <bool SWAP, int MI>
; DI void gemm_main(const bf16_t* __restrict__ A, int lda, const bf16_t* __restrict__ B, int ldb, int K, char* smem, f32x16 (&acc)[MI][2]) {
;     ...
; #pragma unroll
;         for (int s = 0; s < 4; ++s) {
;             bf16x8 af[MI], bfr[2];
; #pragma unroll
;             for (int i = 0; i < MI; ++i) af[i] = *(const bf16x8*)(sA + (wm * (MI * 32) + i * 32 + l31) * GLD + s * 16 + h * 8);
; #pragma unroll
;             for (int j = 0; j < 2; ++j) bfr[j] = *(const bf16x8*)(sB + (wn * 64 + j * 32 + l31) * GLD + s * 16 + h * 8);
; #pragma unroll
;             for (int i = 0; i < MI; ++i)
; #pragma unroll
;                 for (int j = 0; j < 2; ++j) {
;                     if (SWAP) acc[i][j] = MFMA(bfr[j], af[i], acc[i][j]);
;                     else acc[i][j] = MFMA(af[i], bfr[j], acc[i][j]);
;                 }
;         }
;         __syncthreads();
;         if (more) {
; #pragma unroll
;             for (int i = 0; i < 2 * MI; ++i) *(u32x4*)(sA + (lr + 32 * i) * GLD + lc) = ra[i];
; #pragma unroll
;             for (int i = 0; i < 4; ++i) *(u32x4*)(sB + (lr + 32 * i) * GLD + lc) = rb[i];
;         }
;         __syncthreads();
; template <int MI>
; DI void epi_vt_store(const f32x16 (&acc)[MI][2], bf16_t* __restrict__ dstT, int C, int c0, int m0, const float* rowscale) {
;     ...
;                 const int ml = wm * (MI * 32) + i * 32 + 8 * g + 4 * h;
;                 float v0 = acc[i][j][4 * g], v1 = acc[i][j][4 * g + 1], v2 = acc[i][j][4 * g + 2], v3 = acc[i][j][4 * g + 3];
;                 float v4 = acc[i][j][4 * g + 4], v5 = acc[i][j][4 * g + 5], v6 = acc[i][j][4 * g + 6], v7 = acc[i][j][4 * g + 7];
;                 if (rowscale) {
;                     v0 *= rowscale[ml]; v1 *= rowscale[ml + 1]; v2 *= rowscale[ml + 2]; v3 *= rowscale[ml + 3];
;                     v4 *= rowscale[ml + 8]; v5 *= rowscale[ml + 9]; v6 *= rowscale[ml + 10]; v7 *= rowscale[ml + 11];
	s_waitcnt vmcnt(7)
	ds_write_b128 v120, v[72:75]
	s_waitcnt vmcnt(6)
	ds_write_b128 v120, v[76:79] offset:4608
	s_waitcnt vmcnt(5)
	ds_write_b128 v120, v[80:83] offset:9216
	s_waitcnt vmcnt(4)
	ds_write_b128 v120, v[88:91] offset:13824
	s_waitcnt vmcnt(3)
	ds_write_b128 v120, v[104:107] offset:18432
	s_waitcnt vmcnt(2)
	ds_write_b128 v120, v[108:111] offset:23040
	s_waitcnt vmcnt(1)
	ds_write_b128 v120, v[84:87] offset:27648
	s_waitcnt vmcnt(0)
	ds_write_b128 v120, v[112:115] offset:32256
	v_mfma_f32_32x32x16_bf16 v[2:17], v[100:103], v[96:99], v[2:17]
	s_waitcnt lgkmcnt(0)
	s_barrier
	ds_read_b128 v[140:143], v122
	ds_read_b128 v[144:147], v0 offset:18432
	ds_read_b128 v[148:151], v122 offset:32
	ds_read_b128 v[152:155], v0 offset:18464
	ds_read_b128 v[156:159], v0 offset:23040
	ds_read_b128 v[160:163], v0 offset:23072
	ds_read_b128 v[136:139], v122 offset:4608
	ds_read_b128 v[100:103], v122 offset:4640
	ds_read_b128 v[72:75], v122 offset:64
	ds_read_b128 v[76:79], v0 offset:18496
	ds_read_b128 v[80:83], v122 offset:96
	ds_read_b128 v[84:87], v0 offset:18528
	ds_read_b128 v[88:91], v0 offset:23104
	ds_read_b128 v[96:99], v0 offset:23136
	s_waitcnt lgkmcnt(12)
	v_mfma_f32_32x32x16_bf16 v[50:65], v[140:143], v[144:147], v[50:65]
	s_waitcnt lgkmcnt(9)
	v_mfma_f32_32x32x16_bf16 v[18:33], v[140:143], v[156:159], v[18:33]
	s_waitcnt lgkmcnt(7)
	v_mfma_f32_32x32x16_bf16 v[34:49], v[136:139], v[144:147], v[34:49]
	v_mfma_f32_32x32x16_bf16 v[2:17], v[136:139], v[156:159], v[2:17]
	v_mfma_f32_32x32x16_bf16 v[50:65], v[148:151], v[152:155], v[50:65]
	v_mfma_f32_32x32x16_bf16 v[18:33], v[148:151], v[160:163], v[18:33]
	s_waitcnt lgkmcnt(6)
	v_mfma_f32_32x32x16_bf16 v[34:49], v[100:103], v[152:155], v[34:49]
	v_mfma_f32_32x32x16_bf16 v[2:17], v[100:103], v[160:163], v[2:17]
	s_waitcnt lgkmcnt(4)
	v_mfma_f32_32x32x16_bf16 v[50:65], v[72:75], v[76:79], v[50:65]
	s_waitcnt lgkmcnt(1)
	v_mfma_f32_32x32x16_bf16 v[18:33], v[72:75], v[88:91], v[18:33]
	s_waitcnt lgkmcnt(0)
	ds_read_b128 v[72:75], v122 offset:4672
	ds_read_b128 v[100:103], v122 offset:4704
	s_waitcnt lgkmcnt(0)
	s_barrier
	s_barrier
	v_mfma_f32_32x32x16_bf16 v[34:49], v[72:75], v[76:79], v[34:49]
	v_mfma_f32_32x32x16_bf16 v[2:17], v[72:75], v[88:91], v[2:17]
	v_mov_b32_e32 v73, v196
	v_cndmask_b32_e64 v75, 0, 1, s[16:17]
	v_bfe_u32 v0, v73, 5, 1
	v_ashrrev_i32_e32 v72, 1, v73
	v_and_b32_e32 v72, 0xffffffc0, v72
	v_lshl_or_b32 v74, v0, 4, v203
	v_mfma_f32_32x32x16_bf16 v[50:65], v[80:83], v[84:87], v[50:65]
	v_cmp_ne_u32_e64 s[0:1], 1, v75
	v_lshl_add_u32 v78, v72, 2, v74
	v_mfma_f32_32x32x16_bf16 v[18:33], v[80:83], v[96:99], v[18:33]
	v_mfma_f32_32x32x16_bf16 v[34:49], v[100:103], v[84:87], v[34:49]
	v_mfma_f32_32x32x16_bf16 v[2:17], v[100:103], v[96:99], v[2:17]
	s_cbranch_vccnz .LBB0_1479
	ds_read_b128 v[74:77], v78
	ds_read_b128 v[80:83], v78 offset:32
	s_waitcnt lgkmcnt(1)
	s_nop 2
	v_pk_mul_f32 v[50:51], v[50:51], v[74:75]
	v_pk_mul_f32 v[52:53], v[52:53], v[76:77]
	s_waitcnt lgkmcnt(0)
	v_pk_mul_f32 v[54:55], v[54:55], v[80:81]
	v_pk_mul_f32 v[56:57], v[56:57], v[82:83]

; #define MFMA(a, b, c) __builtin_amdgcn_mfma_f32_32x32x16_bf16((a), (b), (c), 0, 0, 0)
; template <bool SWAP, int MI>
; DI void gemm_main(const bf16_t* __restrict__ A, int lda, const bf16_t* __restrict__ B, int ldb, int K, char* smem, f32x16 (&acc)[MI][2]) {
;     ...
;     const int lr = tid >> 3, lc = (tid & 7) * 8;
;     const bf16_t* ap = A + (size_t)lr * lda + lc;
;     const bf16_t* bp = B + (size_t)lr * ldb + lc;
; #pragma unroll
;     for (int i = 0; i < 2 * MI; ++i) ra[i] = *(const u32x4*)(ap + (size_t)(32 * i) * lda);
; #pragma unroll
;     for (int i = 0; i < 4; ++i) rb[i] = *(const u32x4*)(bp + (size_t)(32 * i) * ldb);
;     __syncthreads();
; #pragma unroll
;     for (int i = 0; i < 2 * MI; ++i) *(u32x4*)(sA + (lr + 32 * i) * GLD + lc) = ra[i];
; #pragma unroll
;     for (int i = 0; i < 4; ++i) *(u32x4*)(sB + (lr + 32 * i) * GLD + lc) = rb[i];
;     __syncthreads();
;     for (int k0 = 0; k0 < K; k0 += 64) {
;         const bool more = (k0 + 64) < K;
;         if (more) {
; #pragma unroll
;             for (int i = 0; i < 2 * MI; ++i) ra[i] = *(const u32x4*)(ap + (size_t)(32 * i) * lda + k0 + 64);
; #pragma unroll
;             for (int i = 0; i < 4; ++i) rb[i] = *(const u32x4*)(bp + (size_t)(32 * i) * ldb + k0 + 64);
;         }
; #pragma unroll
;         for (int s = 0; s < 4; ++s) {
;             bf16x8 af[MI], bfr[2];
; #pragma unroll
;             for (int i = 0; i < MI; ++i) af[i] = *(const bf16x8*)(sA + (wm * (MI * 32) + i * 32 + l31) * GLD + s * 16 + h * 8);
; #pragma unroll
;             for (int j = 0; j < 2; ++j) bfr[j] = *(const bf16x8*)(sB + (wn * 64 + j * 32 + l31) * GLD + s * 16 + h * 8);
; #pragma unroll
;             for (int i = 0; i < MI; ++i)
; #pragma unroll
;                 for (int j = 0; j < 2; ++j) {
;                     if (SWAP) acc[i][j] = MFMA(bfr[j], af[i], acc[i][j]);
;                     else acc[i][j] = MFMA(af[i], bfr[j], acc[i][j]);
;                 }
;         }
;         __syncthreads();
;         if (more) {
; #pragma unroll
;             for (int i = 0; i < 2 * MI; ++i) *(u32x4*)(sA + (lr + 32 * i) * GLD + lc) = ra[i];
; #pragma unroll
;             for (int i = 0; i < 4; ++i) *(u32x4*)(sB + (lr + 32 * i) * GLD + lc) = rb[i];
;         }
;         __syncthreads();
.LBB0_1494:
	s_and_b64 vcc, exec, s[0:1]
	s_cbranch_vccz .LBB0_1500
	v_mov_b32_e32 v36, v196
	s_movk_i32 s0, 0x2000
	v_ashrrev_i32_e32 v34, 3, v36
	v_ashrrev_i32_e32 v35, 31, v34
	v_lshlrev_b64 v[2:3], 8, v[34:35]
	v_lshlrev_b32_e32 v0, 4, v36
	v_lshl_add_u64 v[4:5], s[12:13], 0, v[2:3]
	v_and_b32_e32 v0, 0x70, v0
	v_lshl_add_u64 v[104:105], v[4:5], 0, v[0:1]
	v_add_co_u32_e32 v106, vcc, 0x2000, v104
	v_lshl_add_u64 v[18:19], s[10:11], 0, v[2:3]
	s_nop 0
	v_addc_co_u32_e32 v107, vcc, 0, v105, vcc
	v_add_co_u32_e32 v108, vcc, 0x4000, v104
	v_lshl_add_u64 v[112:113], v[18:19], 0, v[0:1]
	s_nop 0
	v_addc_co_u32_e32 v109, vcc, 0, v105, vcc
	v_add_co_u32_e32 v110, vcc, 0x6000, v104
	global_load_dwordx4 v[2:5], v[104:105], off
	global_load_dwordx4 v[6:9], v[106:107], off
	v_addc_co_u32_e32 v111, vcc, 0, v105, vcc
	v_add_co_u32_e32 v114, vcc, s0, v112
	s_movk_i32 s0, 0x6000
	s_nop 0
	v_addc_co_u32_e32 v115, vcc, 0, v113, vcc
	v_add_co_u32_e32 v116, vcc, s52, v112
	global_load_dwordx4 v[10:13], v[108:109], off
	global_load_dwordx4 v[14:17], v[110:111], off
	v_addc_co_u32_e32 v117, vcc, 0, v113, vcc
	v_add_co_u32_e32 v118, vcc, s0, v112
	global_load_dwordx4 v[18:21], v[112:113], off
	global_load_dwordx4 v[22:25], v[114:115], off
	v_addc_co_u32_e32 v119, vcc, 0, v113, vcc
	global_load_dwordx4 v[26:29], v[116:117], off
	global_load_dwordx4 v[30:33], v[118:119], off
	v_lshrrev_b32_e32 v37, 1, v36
	v_and_b32_e32 v35, 31, v36
	v_and_b32_e32 v38, 0x5f, v36
	v_and_b32_e32 v36, 16, v37
	v_mad_u64_u32 v[120:121], s[0:1], v34, s35, v[0:1]
	v_mad_u32_u24 v0, v38, s35, v36
	s_waitcnt lgkmcnt(0)
	s_barrier
	s_mov_b32 s0, 0xfffffc0
	s_mov_b64 s[10:11], -1
	s_andn2_b64 vcc, exec, s[10:11]
	s_waitcnt vmcnt(7)
	ds_write_b128 v120, v[2:5]
	s_waitcnt vmcnt(3)
	ds_write_b128 v120, v[18:21] offset:18432
	ds_write_b128 v120, v[6:9] offset:4608
	ds_write_b128 v120, v[10:13] offset:9216
	ds_write_b128 v120, v[14:17] offset:13824
	s_waitcnt vmcnt(2)
	ds_write_b128 v120, v[22:25] offset:23040
	s_waitcnt vmcnt(1)
	ds_write_b128 v120, v[26:29] offset:27648
	s_waitcnt vmcnt(0)
	ds_write_b128 v120, v[30:33] offset:32256
	s_waitcnt lgkmcnt(0)
	s_barrier
	ds_read_b128 v[2:5], v0 offset:18432
	v_and_or_b32 v6, v37, s0, v35
	v_mad_u64_u32 v[122:123], s[0:1], v6, s35, v[36:37]
	ds_read_b128 v[6:9], v122
	ds_read_b128 v[72:75], v122 offset:32
	ds_read_b128 v[76:79], v0 offset:18464
	ds_read_b128 v[10:13], v0 offset:23040
	ds_read_b128 v[80:83], v0 offset:23072
	s_waitcnt lgkmcnt(4)
	v_mfma_f32_32x32x16_bf16 v[50:65], v[2:5], v[6:9], 0
	s_movk_i32 s0, 0xffc0
	s_waitcnt lgkmcnt(1)
	v_mfma_f32_32x32x16_bf16 v[34:49], v[10:13], v[6:9], 0
	ds_read_b128 v[6:9], v122 offset:4608
	ds_read_b128 v[84:87], v122 offset:4640
	s_waitcnt lgkmcnt(1)
	v_mfma_f32_32x32x16_bf16 v[18:33], v[2:5], v[6:9], 0
	v_mfma_f32_32x32x16_bf16 v[2:17], v[10:13], v[6:9], 0
	v_mfma_f32_32x32x16_bf16 v[50:65], v[76:79], v[72:75], v[50:65]
	v_mfma_f32_32x32x16_bf16 v[34:49], v[80:83], v[72:75], v[34:49]
	s_waitcnt lgkmcnt(0)
	v_mfma_f32_32x32x16_bf16 v[18:33], v[76:79], v[84:87], v[18:33]
	v_mfma_f32_32x32x16_bf16 v[2:17], v[80:83], v[84:87], v[2:17]
	ds_read_b128 v[72:75], v0 offset:18496
	ds_read_b128 v[76:79], v122 offset:64
	ds_read_b128 v[80:83], v122 offset:96
	ds_read_b128 v[84:87], v0 offset:18528
	ds_read_b128 v[88:91], v0 offset:23104
	ds_read_b128 v[96:99], v0 offset:23136
	s_waitcnt lgkmcnt(4)
	v_mfma_f32_32x32x16_bf16 v[50:65], v[72:75], v[76:79], v[50:65]
	s_waitcnt lgkmcnt(1)
	v_mfma_f32_32x32x16_bf16 v[34:49], v[88:91], v[76:79], v[34:49]
	ds_read_b128 v[76:79], v122 offset:4672
	ds_read_b128 v[100:103], v122 offset:4704
	s_waitcnt lgkmcnt(1)
	v_mfma_f32_32x32x16_bf16 v[18:33], v[72:75], v[76:79], v[18:33]
	v_mfma_f32_32x32x16_bf16 v[2:17], v[88:91], v[76:79], v[2:17]
	v_mfma_f32_32x32x16_bf16 v[50:65], v[84:87], v[80:83], v[50:65]
	v_mfma_f32_32x32x16_bf16 v[34:49], v[96:99], v[80:83], v[34:49]
	global_load_dwordx4 v[72:75], v[104:105], off offset:128
	global_load_dwordx4 v[76:79], v[106:107], off offset:128
	global_load_dwordx4 v[80:83], v[108:109], off offset:128
	global_load_dwordx4 v[88:91], v[110:111], off offset:128
	s_nop 0
	global_load_dwordx4 v[104:107], v[112:113], off offset:128
	global_load_dwordx4 v[108:111], v[114:115], off offset:128
	s_waitcnt lgkmcnt(0)
	v_mfma_f32_32x32x16_bf16 v[18:33], v[84:87], v[100:103], v[18:33]
	global_load_dwordx4 v[84:87], v[116:117], off offset:128
	global_load_dwordx4 v[112:115], v[118:119], off offset:128
	s_barrier
; #define MFMA(a, b, c) __builtin_amdgcn_mfma_f32_32x32x16_bf16((a), (b), (c), 0, 0, 0)
; template <bool SWAP, int MI>
; DI void gemm_main(const bf16_t* __restrict__ A, int lda, const bf16_t* __restrict__ B, int ldb, int K, char* smem, f32x16 (&acc)[MI][2]) {
;     ...
; #pragma unroll
;         for (int s = 0; s < 4; ++s) {
;             bf16x8 af[MI], bfr[2];
; #pragma unroll
;             for (int i = 0; i < MI; ++i) af[i] = *(const bf16x8*)(sA + (wm * (MI * 32) + i * 32 + l31) * GLD + s * 16 + h * 8);
; #pragma unroll
;             for (int j = 0; j < 2; ++j) bfr[j] = *(const bf16x8*)(sB + (wn * 64 + j * 32 + l31) * GLD + s * 16 + h * 8);
; #pragma unroll
;             for (int i = 0; i < MI; ++i)
; #pragma unroll
;                 for (int j = 0; j < 2; ++j) {
;                     if (SWAP) acc[i][j] = MFMA(bfr[j], af[i], acc[i][j]);
;                     else acc[i][j] = MFMA(af[i], bfr[j], acc[i][j]);
;                 }
;         }
;         __syncthreads();
;         if (more) {
; #pragma unroll
;             for (int i = 0; i < 2 * MI; ++i) *(u32x4*)(sA + (lr + 32 * i) * GLD + lc) = ra[i];
; #pragma unroll
;             for (int i = 0; i < 4; ++i) *(u32x4*)(sB + (lr + 32 * i) * GLD + lc) = rb[i];
;         }
;         __syncthreads();
; template <int MI>
; DI void epi_swap_store(const f32x16 (&acc)[MI][2], bf16_t* __restrict__ dst, int ld, int col0, int m0, int rope, int ropemask,
;                        const float* __restrict__ cs, const float* rowscale, bool wn_only0) {
;     ...
;         const int ml = wm * (MI * 32) + i * 32 + l31;
;         const int m = m0 + ml;
;         const float rs = rowscale ? rowscale[ml] : 1.f;
; #pragma unroll
;         for (int j = 0; j < 2; ++j) {
;             f32x16 v = acc[i][j];
; #pragma unroll
;             for (int r = 0; r < 16; ++r) v[r] *= rs;
	s_waitcnt vmcnt(7)
	ds_write_b128 v120, v[72:75]
	s_waitcnt vmcnt(6)
	ds_write_b128 v120, v[76:79] offset:4608
	s_waitcnt vmcnt(5)
	ds_write_b128 v120, v[80:83] offset:9216
	s_waitcnt vmcnt(4)
	ds_write_b128 v120, v[88:91] offset:13824
	s_waitcnt vmcnt(3)
	ds_write_b128 v120, v[104:107] offset:18432
	s_waitcnt vmcnt(2)
	ds_write_b128 v120, v[108:111] offset:23040
	s_waitcnt vmcnt(1)
	ds_write_b128 v120, v[84:87] offset:27648
	s_waitcnt vmcnt(0)
	ds_write_b128 v120, v[112:115] offset:32256
	v_mfma_f32_32x32x16_bf16 v[2:17], v[96:99], v[100:103], v[2:17]
	s_waitcnt lgkmcnt(0)
	s_barrier
	ds_read_b128 v[136:139], v0 offset:18432
	ds_read_b128 v[144:147], v122
	ds_read_b128 v[148:151], v122 offset:32
	ds_read_b128 v[152:155], v0 offset:18464
	ds_read_b128 v[156:159], v0 offset:23040
	ds_read_b128 v[160:163], v0 offset:23072
	ds_read_b128 v[140:143], v122 offset:4608
	ds_read_b128 v[100:103], v122 offset:4640
	ds_read_b128 v[72:75], v0 offset:18496
	ds_read_b128 v[76:79], v122 offset:64
	ds_read_b128 v[80:83], v122 offset:96
	ds_read_b128 v[84:87], v0 offset:18528
	ds_read_b128 v[88:91], v0 offset:23104
	ds_read_b128 v[96:99], v0 offset:23136
	s_waitcnt lgkmcnt(12)
	v_mfma_f32_32x32x16_bf16 v[50:65], v[136:139], v[144:147], v[50:65]
	s_waitcnt lgkmcnt(9)
	v_mfma_f32_32x32x16_bf16 v[34:49], v[156:159], v[144:147], v[34:49]
	s_waitcnt lgkmcnt(7)
	v_mfma_f32_32x32x16_bf16 v[18:33], v[136:139], v[140:143], v[18:33]
	v_mfma_f32_32x32x16_bf16 v[2:17], v[156:159], v[140:143], v[2:17]
	v_mfma_f32_32x32x16_bf16 v[50:65], v[152:155], v[148:151], v[50:65]
	v_mfma_f32_32x32x16_bf16 v[34:49], v[160:163], v[148:151], v[34:49]
	s_waitcnt lgkmcnt(6)
	v_mfma_f32_32x32x16_bf16 v[18:33], v[152:155], v[100:103], v[18:33]
	v_mfma_f32_32x32x16_bf16 v[2:17], v[160:163], v[100:103], v[2:17]
	s_waitcnt lgkmcnt(4)
	v_mfma_f32_32x32x16_bf16 v[50:65], v[72:75], v[76:79], v[50:65]
	s_waitcnt lgkmcnt(1)
	v_mfma_f32_32x32x16_bf16 v[34:49], v[88:91], v[76:79], v[34:49]
	s_waitcnt lgkmcnt(0)
	ds_read_b128 v[76:79], v122 offset:4672
	ds_read_b128 v[100:103], v122 offset:4704
	s_waitcnt lgkmcnt(0)
	s_barrier
	s_barrier
	v_mfma_f32_32x32x16_bf16 v[18:33], v[72:75], v[76:79], v[18:33]
	v_mov_b32_e32 v74, v196
	s_nop 0
	v_and_b32_e32 v0, 31, v74
	v_ashrrev_i32_e32 v72, 1, v74
	v_and_or_b32 v73, v72, s0, v0
	v_cndmask_b32_e64 v0, 0, 1, s[10:11]
	v_mfma_f32_32x32x16_bf16 v[2:17], v[88:91], v[76:79], v[2:17]
	v_mov_b32_e32 v72, 1.0
	v_cmp_ne_u32_e64 s[0:1], 1, v0
	v_mov_b32_e32 v76, 1.0
	v_mfma_f32_32x32x16_bf16 v[50:65], v[84:87], v[80:83], v[50:65]
	v_mfma_f32_32x32x16_bf16 v[34:49], v[96:99], v[80:83], v[34:49]
	v_mfma_f32_32x32x16_bf16 v[18:33], v[84:87], v[100:103], v[18:33]
	v_mfma_f32_32x32x16_bf16 v[2:17], v[96:99], v[100:103], v[2:17]
	s_cbranch_vccnz .LBB0_1497
	v_lshl_add_u32 v0, v73, 2, v203
	ds_read_b32 v76, v0

; #define MFMA(a, b, c) __builtin_amdgcn_mfma_f32_32x32x16_bf16((a), (b), (c), 0, 0, 0)
; template <bool SWAP, int MI>
; DI void gemm_main(const bf16_t* __restrict__ A, int lda, const bf16_t* __restrict__ B, int ldb, int K, char* smem, f32x16 (&acc)[MI][2]) {
;     ...
;     const int lr = tid >> 3, lc = (tid & 7) * 8;
;     const bf16_t* ap = A + (size_t)lr * lda + lc;
;     const bf16_t* bp = B + (size_t)lr * ldb + lc;
; #pragma unroll
;     for (int i = 0; i < 2 * MI; ++i) ra[i] = *(const u32x4*)(ap + (size_t)(32 * i) * lda);
; #pragma unroll
;     for (int i = 0; i < 4; ++i) rb[i] = *(const u32x4*)(bp + (size_t)(32 * i) * ldb);
;     __syncthreads();
; #pragma unroll
;     for (int i = 0; i < 2 * MI; ++i) *(u32x4*)(sA + (lr + 32 * i) * GLD + lc) = ra[i];
; #pragma unroll
;     for (int i = 0; i < 4; ++i) *(u32x4*)(sB + (lr + 32 * i) * GLD + lc) = rb[i];
;     __syncthreads();
;     for (int k0 = 0; k0 < K; k0 += 64) {
;         const bool more = (k0 + 64) < K;
;         if (more) {
; #pragma unroll
;             for (int i = 0; i < 2 * MI; ++i) ra[i] = *(const u32x4*)(ap + (size_t)(32 * i) * lda + k0 + 64);
; #pragma unroll
;             for (int i = 0; i < 4; ++i) rb[i] = *(const u32x4*)(bp + (size_t)(32 * i) * ldb + k0 + 64);
;         }
; #pragma unroll
;         for (int s = 0; s < 4; ++s) {
;             bf16x8 af[MI], bfr[2];
; #pragma unroll
;             for (int i = 0; i < MI; ++i) af[i] = *(const bf16x8*)(sA + (wm * (MI * 32) + i * 32 + l31) * GLD + s * 16 + h * 8);
; #pragma unroll
;             for (int j = 0; j < 2; ++j) bfr[j] = *(const bf16x8*)(sB + (wn * 64 + j * 32 + l31) * GLD + s * 16 + h * 8);
; #pragma unroll
;             for (int i = 0; i < MI; ++i)
; #pragma unroll
;                 for (int j = 0; j < 2; ++j) {
;                     if (SWAP) acc[i][j] = MFMA(bfr[j], af[i], acc[i][j]);
;                     else acc[i][j] = MFMA(af[i], bfr[j], acc[i][j]);
;                 }
;         }
;         __syncthreads();
;         if (more) {
; #pragma unroll
;             for (int i = 0; i < 2 * MI; ++i) *(u32x4*)(sA + (lr + 32 * i) * GLD + lc) = ra[i];
; #pragma unroll
;             for (int i = 0; i < 4; ++i) *(u32x4*)(sB + (lr + 32 * i) * GLD + lc) = rb[i];
;         }
;         __syncthreads();
.LBB0_1506:
	s_or_b64 exec, exec, s[0:1]
	s_mul_i32 s0, s12, 6
	v_mov_b32_e32 v36, v196
	s_sub_i32 s0, s11, s0
	s_lshl_b32 s1, s12, 16
	v_readlane_b32 s8, v245, 11
	s_add_u32 s8, s8, s1
	v_ashrrev_i32_e32 v34, 3, v36
	v_readlane_b32 s1, v245, 12
	v_ashrrev_i32_e32 v35, 31, v34
	s_addc_u32 s9, s1, 0
	v_lshlrev_b64 v[2:3], 9, v[34:35]
	v_lshlrev_b32_e32 v0, 4, v36
	v_lshl_add_u64 v[4:5], s[8:9], 0, v[2:3]
	v_and_b32_e32 v0, 0x70, v0
	v_lshl_add_u64 v[72:73], v[4:5], 0, v[0:1]
	v_add_co_u32_e32 v74, vcc, s52, v72
	s_lshl_b32 s1, s0, 16
	s_nop 0
	v_addc_co_u32_e32 v75, vcc, 0, v73, vcc
	s_add_u32 s12, s23, s1
	v_add_co_u32_e32 v76, vcc, s24, v72
	s_addc_u32 s13, s48, 0
	s_nop 0
	v_addc_co_u32_e32 v77, vcc, 0, v73, vcc
	s_mov_b32 s1, 0xc000
	v_lshl_add_u64 v[18:19], s[12:13], 0, v[2:3]
	v_add_co_u32_e32 v78, vcc, s1, v72
	v_lshl_add_u64 v[82:83], v[18:19], 0, v[0:1]
	s_nop 0
	v_addc_co_u32_e32 v79, vcc, 0, v73, vcc
	v_add_co_u32_e32 v84, vcc, s52, v82
	global_load_dwordx4 v[2:5], v[72:73], off
	global_load_dwordx4 v[6:9], v[74:75], off
	v_addc_co_u32_e32 v85, vcc, 0, v83, vcc
	v_add_co_u32_e32 v86, vcc, s24, v82
	global_load_dwordx4 v[10:13], v[76:77], off
	global_load_dwordx4 v[14:17], v[78:79], off
	v_addc_co_u32_e32 v87, vcc, 0, v83, vcc
	v_add_co_u32_e32 v88, vcc, s1, v82
	global_load_dwordx4 v[18:21], v[82:83], off
	global_load_dwordx4 v[22:25], v[84:85], off
	v_addc_co_u32_e32 v89, vcc, 0, v83, vcc
	global_load_dwordx4 v[26:29], v[86:87], off
	global_load_dwordx4 v[30:33], v[88:89], off
	v_lshrrev_b32_e32 v37, 1, v36
	v_and_b32_e32 v35, 31, v36
	v_and_b32_e32 v38, 0x5f, v36
	v_and_b32_e32 v36, 16, v37
	v_mad_u64_u32 v[90:91], s[8:9], v34, s35, v[0:1]
	v_mad_u32_u24 v0, v38, s35, v36
	s_waitcnt lgkmcnt(0)
	s_barrier
	s_mov_b32 s1, 0xfffffc0
	s_waitcnt vmcnt(7)
	ds_write_b128 v90, v[2:5]
	s_waitcnt vmcnt(6)
	ds_write_b128 v90, v[6:9] offset:4608
	s_waitcnt vmcnt(5)
	ds_write_b128 v90, v[10:13] offset:9216
	s_waitcnt vmcnt(4)
	ds_write_b128 v90, v[14:17] offset:13824
	s_waitcnt vmcnt(3)
	ds_write_b128 v90, v[18:21] offset:18432
	s_waitcnt vmcnt(2)
	ds_write_b128 v90, v[22:25] offset:23040
	s_waitcnt vmcnt(1)
	ds_write_b128 v90, v[26:29] offset:27648
	s_waitcnt vmcnt(0)
	ds_write_b128 v90, v[30:33] offset:32256
	s_waitcnt lgkmcnt(0)
	s_barrier
	ds_read_b128 v[2:5], v0 offset:18432
	v_and_or_b32 v6, v37, s1, v35
	v_mad_u64_u32 v[80:81], s[8:9], v6, s35, v[36:37]
	ds_read_b128 v[6:9], v80
	ds_read_b128 v[96:99], v80 offset:32
	ds_read_b128 v[100:103], v0 offset:18464
	ds_read_b128 v[10:13], v0 offset:23040
	ds_read_b128 v[104:107], v0 offset:23072
	s_waitcnt lgkmcnt(4)
	v_mfma_f32_32x32x16_bf16 v[50:65], v[2:5], v[6:9], 0
	s_movk_i32 s1, 0xffc0
	s_mov_b64 s[8:9], -1
	s_andn2_b64 vcc, exec, s[8:9]
	s_waitcnt lgkmcnt(1)
	v_mfma_f32_32x32x16_bf16 v[34:49], v[10:13], v[6:9], 0
	ds_read_b128 v[6:9], v80 offset:4608
	ds_read_b128 v[108:111], v80 offset:4640
	s_waitcnt lgkmcnt(1)
	v_mfma_f32_32x32x16_bf16 v[18:33], v[2:5], v[6:9], 0
	v_mfma_f32_32x32x16_bf16 v[2:17], v[10:13], v[6:9], 0
	v_mfma_f32_32x32x16_bf16 v[50:65], v[100:103], v[96:99], v[50:65]
	v_mfma_f32_32x32x16_bf16 v[34:49], v[104:107], v[96:99], v[34:49]
	s_waitcnt lgkmcnt(0)
	v_mfma_f32_32x32x16_bf16 v[18:33], v[100:103], v[108:111], v[18:33]
	v_mfma_f32_32x32x16_bf16 v[2:17], v[104:107], v[108:111], v[2:17]
	ds_read_b128 v[96:99], v0 offset:18496
	ds_read_b128 v[100:103], v80 offset:64
	ds_read_b128 v[104:107], v80 offset:96
	ds_read_b128 v[108:111], v0 offset:18528
	ds_read_b128 v[112:115], v0 offset:23104
	ds_read_b128 v[116:119], v0 offset:23136
	s_waitcnt lgkmcnt(4)
	v_mfma_f32_32x32x16_bf16 v[50:65], v[96:99], v[100:103], v[50:65]
	s_waitcnt lgkmcnt(1)
	v_mfma_f32_32x32x16_bf16 v[34:49], v[112:115], v[100:103], v[34:49]
	ds_read_b128 v[100:103], v80 offset:4672
	ds_read_b128 v[120:123], v80 offset:4704
	s_waitcnt lgkmcnt(1)
	v_mfma_f32_32x32x16_bf16 v[18:33], v[96:99], v[100:103], v[18:33]
	v_mfma_f32_32x32x16_bf16 v[2:17], v[112:115], v[100:103], v[2:17]
	v_mfma_f32_32x32x16_bf16 v[50:65], v[108:111], v[104:107], v[50:65]
	v_mfma_f32_32x32x16_bf16 v[34:49], v[116:119], v[104:107], v[34:49]
	global_load_dwordx4 v[96:99], v[72:73], off offset:128
	global_load_dwordx4 v[100:103], v[74:75], off offset:128
	global_load_dwordx4 v[104:107], v[76:77], off offset:128
	global_load_dwordx4 v[112:115], v[78:79], off offset:128
	global_load_dwordx4 v[124:127], v[82:83], off offset:128
	global_load_dwordx4 v[128:131], v[84:85], off offset:128
	s_waitcnt lgkmcnt(0)
	v_mfma_f32_32x32x16_bf16 v[18:33], v[108:111], v[120:123], v[18:33]
	global_load_dwordx4 v[108:111], v[86:87], off offset:128
	global_load_dwordx4 v[132:135], v[88:89], off offset:128
	s_barrier
	s_waitcnt vmcnt(7)
	ds_write_b128 v90, v[96:99]
	s_waitcnt vmcnt(6)
	ds_write_b128 v90, v[100:103] offset:4608
	s_waitcnt vmcnt(5)
	ds_write_b128 v90, v[104:107] offset:9216
	s_waitcnt vmcnt(4)
	ds_write_b128 v90, v[112:115] offset:13824
	s_waitcnt vmcnt(3)
	ds_write_b128 v90, v[124:127] offset:18432
	s_waitcnt vmcnt(2)
	ds_write_b128 v90, v[128:131] offset:23040
	s_waitcnt vmcnt(1)
	ds_write_b128 v90, v[108:111] offset:27648
	s_waitcnt vmcnt(0)
	ds_write_b128 v90, v[132:135] offset:32256
	v_mfma_f32_32x32x16_bf16 v[2:17], v[116:119], v[120:123], v[2:17]
	s_waitcnt lgkmcnt(0)
	s_barrier
; #define MFMA(a, b, c) __builtin_amdgcn_mfma_f32_32x32x16_bf16((a), (b), (c), 0, 0, 0)
; template <bool SWAP, int MI>
; DI void gemm_main(const bf16_t* __restrict__ A, int lda, const bf16_t* __restrict__ B, int ldb, int K, char* smem, f32x16 (&acc)[MI][2]) {
;     ...
;     for (int k0 = 0; k0 < K; k0 += 64) {
;         const bool more = (k0 + 64) < K;
;         if (more) {
; #pragma unroll
;             for (int i = 0; i < 2 * MI; ++i) ra[i] = *(const u32x4*)(ap + (size_t)(32 * i) * lda + k0 + 64);
; #pragma unroll
;             for (int i = 0; i < 4; ++i) rb[i] = *(const u32x4*)(bp + (size_t)(32 * i) * ldb + k0 + 64);
;         }
; #pragma unroll
;         for (int s = 0; s < 4; ++s) {
;             bf16x8 af[MI], bfr[2];
; #pragma unroll
;             for (int i = 0; i < MI; ++i) af[i] = *(const bf16x8*)(sA + (wm * (MI * 32) + i * 32 + l31) * GLD + s * 16 + h * 8);
; #pragma unroll
;             for (int j = 0; j < 2; ++j) bfr[j] = *(const bf16x8*)(sB + (wn * 64 + j * 32 + l31) * GLD + s * 16 + h * 8);
; #pragma unroll
;             for (int i = 0; i < MI; ++i)
; #pragma unroll
;                 for (int j = 0; j < 2; ++j) {
;                     if (SWAP) acc[i][j] = MFMA(bfr[j], af[i], acc[i][j]);
;                     else acc[i][j] = MFMA(af[i], bfr[j], acc[i][j]);
;                 }
;         }
;         __syncthreads();
;         if (more) {
; #pragma unroll
;             for (int i = 0; i < 2 * MI; ++i) *(u32x4*)(sA + (lr + 32 * i) * GLD + lc) = ra[i];
; #pragma unroll
;             for (int i = 0; i < 4; ++i) *(u32x4*)(sB + (lr + 32 * i) * GLD + lc) = rb[i];
;         }
;         __syncthreads();
	ds_read_b128 v[136:139], v0 offset:18432
	ds_read_b128 v[148:151], v80
	ds_read_b128 v[152:155], v80 offset:32
	ds_read_b128 v[156:159], v0 offset:18464
	ds_read_b128 v[160:163], v0 offset:23040
	ds_read_b128 v[164:167], v0 offset:23072
	ds_read_b128 v[144:147], v80 offset:4608
	ds_read_b128 v[168:171], v80 offset:4640
	ds_read_b128 v[96:99], v0 offset:18496
	ds_read_b128 v[140:143], v80 offset:64
	ds_read_b128 v[104:107], v80 offset:96
	ds_read_b128 v[108:111], v0 offset:18528
	ds_read_b128 v[112:115], v0 offset:23104
	ds_read_b128 v[116:119], v0 offset:23136
	ds_read_b128 v[100:103], v80 offset:4672
	ds_read_b128 v[120:123], v80 offset:4704
	s_waitcnt lgkmcnt(14)
	v_mfma_f32_32x32x16_bf16 v[50:65], v[136:139], v[148:151], v[50:65]
	s_waitcnt lgkmcnt(11)
	v_mfma_f32_32x32x16_bf16 v[34:49], v[160:163], v[148:151], v[34:49]
	s_waitcnt lgkmcnt(9)
	v_mfma_f32_32x32x16_bf16 v[18:33], v[136:139], v[144:147], v[18:33]
	v_mfma_f32_32x32x16_bf16 v[2:17], v[160:163], v[144:147], v[2:17]
	v_mfma_f32_32x32x16_bf16 v[50:65], v[156:159], v[152:155], v[50:65]
	v_mfma_f32_32x32x16_bf16 v[34:49], v[164:167], v[152:155], v[34:49]
	s_waitcnt lgkmcnt(8)
	v_mfma_f32_32x32x16_bf16 v[18:33], v[156:159], v[168:171], v[18:33]
	v_mfma_f32_32x32x16_bf16 v[2:17], v[164:167], v[168:171], v[2:17]
	s_waitcnt lgkmcnt(6)
	v_mfma_f32_32x32x16_bf16 v[50:65], v[96:99], v[140:143], v[50:65]
	s_waitcnt lgkmcnt(3)
	v_mfma_f32_32x32x16_bf16 v[34:49], v[112:115], v[140:143], v[34:49]
	s_waitcnt lgkmcnt(1)
	v_mfma_f32_32x32x16_bf16 v[18:33], v[96:99], v[100:103], v[18:33]
	v_mfma_f32_32x32x16_bf16 v[2:17], v[112:115], v[100:103], v[2:17]
	v_mfma_f32_32x32x16_bf16 v[50:65], v[108:111], v[104:107], v[50:65]
	v_mfma_f32_32x32x16_bf16 v[34:49], v[116:119], v[104:107], v[34:49]
	s_waitcnt lgkmcnt(0)
	global_load_dwordx4 v[96:99], v[72:73], off offset:256
	global_load_dwordx4 v[100:103], v[74:75], off offset:256
	global_load_dwordx4 v[104:107], v[76:77], off offset:256
	global_load_dwordx4 v[112:115], v[78:79], off offset:256
	global_load_dwordx4 v[124:127], v[82:83], off offset:256
	global_load_dwordx4 v[128:131], v[84:85], off offset:256
	s_waitcnt lgkmcnt(0)
	v_mfma_f32_32x32x16_bf16 v[18:33], v[108:111], v[120:123], v[18:33]
	global_load_dwordx4 v[108:111], v[86:87], off offset:256
	global_load_dwordx4 v[132:135], v[88:89], off offset:256
	s_barrier
	s_waitcnt vmcnt(7)
	ds_write_b128 v90, v[96:99]
	s_waitcnt vmcnt(6)
	ds_write_b128 v90, v[100:103] offset:4608
	s_waitcnt vmcnt(5)
	ds_write_b128 v90, v[104:107] offset:9216
	s_waitcnt vmcnt(4)
	ds_write_b128 v90, v[112:115] offset:13824
	s_waitcnt vmcnt(3)
	ds_write_b128 v90, v[124:127] offset:18432
	s_waitcnt vmcnt(2)
	ds_write_b128 v90, v[128:131] offset:23040
	s_waitcnt vmcnt(1)
	ds_write_b128 v90, v[108:111] offset:27648
	s_waitcnt vmcnt(0)
	ds_write_b128 v90, v[132:135] offset:32256
	v_mfma_f32_32x32x16_bf16 v[2:17], v[116:119], v[120:123], v[2:17]
	s_waitcnt lgkmcnt(0)
	s_barrier
; #define MFMA(a, b, c) __builtin_amdgcn_mfma_f32_32x32x16_bf16((a), (b), (c), 0, 0, 0)
; template <bool SWAP, int MI>
; DI void gemm_main(const bf16_t* __restrict__ A, int lda, const bf16_t* __restrict__ B, int ldb, int K, char* smem, f32x16 (&acc)[MI][2]) {
;     ...
;     for (int k0 = 0; k0 < K; k0 += 64) {
;         const bool more = (k0 + 64) < K;
;         if (more) {
; #pragma unroll
;             for (int i = 0; i < 2 * MI; ++i) ra[i] = *(const u32x4*)(ap + (size_t)(32 * i) * lda + k0 + 64);
; #pragma unroll
;             for (int i = 0; i < 4; ++i) rb[i] = *(const u32x4*)(bp + (size_t)(32 * i) * ldb + k0 + 64);
;         }
; #pragma unroll
;         for (int s = 0; s < 4; ++s) {
;             bf16x8 af[MI], bfr[2];
; #pragma unroll
;             for (int i = 0; i < MI; ++i) af[i] = *(const bf16x8*)(sA + (wm * (MI * 32) + i * 32 + l31) * GLD + s * 16 + h * 8);
; #pragma unroll
;             for (int j = 0; j < 2; ++j) bfr[j] = *(const bf16x8*)(sB + (wn * 64 + j * 32 + l31) * GLD + s * 16 + h * 8);
; #pragma unroll
;             for (int i = 0; i < MI; ++i)
; #pragma unroll
;                 for (int j = 0; j < 2; ++j) {
;                     if (SWAP) acc[i][j] = MFMA(bfr[j], af[i], acc[i][j]);
;                     else acc[i][j] = MFMA(af[i], bfr[j], acc[i][j]);
;                 }
;         }
;         __syncthreads();
;         if (more) {
; #pragma unroll
;             for (int i = 0; i < 2 * MI; ++i) *(u32x4*)(sA + (lr + 32 * i) * GLD + lc) = ra[i];
; #pragma unroll
;             for (int i = 0; i < 4; ++i) *(u32x4*)(sB + (lr + 32 * i) * GLD + lc) = rb[i];
;         }
;         __syncthreads();
; template <int MI>
; DI void epi_swap_store(const f32x16 (&acc)[MI][2], bf16_t* __restrict__ dst, int ld, int col0, int m0, int rope, int ropemask,
;                        const float* __restrict__ cs, const float* rowscale, bool wn_only0) {
;     ...
;         const int ml = wm * (MI * 32) + i * 32 + l31;
;         const int m = m0 + ml;
;         const float rs = rowscale ? rowscale[ml] : 1.f;
	ds_read_b128 v[136:139], v0 offset:18432
	ds_read_b128 v[148:151], v80
	ds_read_b128 v[152:155], v80 offset:32
	ds_read_b128 v[156:159], v0 offset:18464
	ds_read_b128 v[160:163], v0 offset:23040
	ds_read_b128 v[164:167], v0 offset:23072
	ds_read_b128 v[144:147], v80 offset:4608
	ds_read_b128 v[168:171], v80 offset:4640
	ds_read_b128 v[96:99], v0 offset:18496
	ds_read_b128 v[140:143], v80 offset:64
	ds_read_b128 v[104:107], v80 offset:96
	ds_read_b128 v[108:111], v0 offset:18528
	ds_read_b128 v[112:115], v0 offset:23104
	ds_read_b128 v[116:119], v0 offset:23136
	ds_read_b128 v[100:103], v80 offset:4672
	ds_read_b128 v[120:123], v80 offset:4704
	s_waitcnt lgkmcnt(14)
	v_mfma_f32_32x32x16_bf16 v[50:65], v[136:139], v[148:151], v[50:65]
	s_waitcnt lgkmcnt(11)
	v_mfma_f32_32x32x16_bf16 v[34:49], v[160:163], v[148:151], v[34:49]
	s_waitcnt lgkmcnt(9)
	v_mfma_f32_32x32x16_bf16 v[18:33], v[136:139], v[144:147], v[18:33]
	v_mfma_f32_32x32x16_bf16 v[2:17], v[160:163], v[144:147], v[2:17]
	v_mfma_f32_32x32x16_bf16 v[50:65], v[156:159], v[152:155], v[50:65]
	v_mfma_f32_32x32x16_bf16 v[34:49], v[164:167], v[152:155], v[34:49]
	s_waitcnt lgkmcnt(8)
	v_mfma_f32_32x32x16_bf16 v[18:33], v[156:159], v[168:171], v[18:33]
	v_mfma_f32_32x32x16_bf16 v[2:17], v[164:167], v[168:171], v[2:17]
	s_waitcnt lgkmcnt(6)
	v_mfma_f32_32x32x16_bf16 v[50:65], v[96:99], v[140:143], v[50:65]
	s_waitcnt lgkmcnt(3)
	v_mfma_f32_32x32x16_bf16 v[34:49], v[112:115], v[140:143], v[34:49]
	s_waitcnt lgkmcnt(1)
	v_mfma_f32_32x32x16_bf16 v[18:33], v[96:99], v[100:103], v[18:33]
	v_mfma_f32_32x32x16_bf16 v[2:17], v[112:115], v[100:103], v[2:17]
	v_mfma_f32_32x32x16_bf16 v[50:65], v[108:111], v[104:107], v[50:65]
	v_mfma_f32_32x32x16_bf16 v[34:49], v[116:119], v[104:107], v[34:49]
	s_waitcnt lgkmcnt(0)
	global_load_dwordx4 v[96:99], v[72:73], off offset:384
	s_nop 0
	global_load_dwordx4 v[72:75], v[74:75], off offset:384
	s_nop 0
	global_load_dwordx4 v[100:103], v[76:77], off offset:384
	s_nop 0
	global_load_dwordx4 v[76:79], v[78:79], off offset:384
	s_nop 0
	global_load_dwordx4 v[104:107], v[82:83], off offset:384
	s_nop 0
	global_load_dwordx4 v[82:85], v[84:85], off offset:384
	s_waitcnt lgkmcnt(0)
	v_mfma_f32_32x32x16_bf16 v[18:33], v[108:111], v[120:123], v[18:33]
	global_load_dwordx4 v[108:111], v[86:87], off offset:384
	s_nop 0
	global_load_dwordx4 v[86:89], v[88:89], off offset:384
	s_barrier
	s_waitcnt vmcnt(7)
	ds_write_b128 v90, v[96:99]
	s_waitcnt vmcnt(6)
	ds_write_b128 v90, v[72:75] offset:4608
	s_waitcnt vmcnt(5)
	ds_write_b128 v90, v[100:103] offset:9216
	s_waitcnt vmcnt(4)
	ds_write_b128 v90, v[76:79] offset:13824
	s_waitcnt vmcnt(3)
	ds_write_b128 v90, v[104:107] offset:18432
	s_waitcnt vmcnt(2)
	ds_write_b128 v90, v[82:85] offset:23040
	s_waitcnt vmcnt(1)
	ds_write_b128 v90, v[108:111] offset:27648
	s_waitcnt vmcnt(0)
	ds_write_b128 v90, v[86:89] offset:32256
	v_mfma_f32_32x32x16_bf16 v[2:17], v[116:119], v[120:123], v[2:17]
	s_waitcnt lgkmcnt(0)
	s_barrier
	ds_read_b128 v[136:139], v0 offset:18432
	ds_read_b128 v[144:147], v80
	ds_read_b128 v[148:151], v80 offset:32
	ds_read_b128 v[152:155], v0 offset:18464
	ds_read_b128 v[96:99], v0 offset:23040
	ds_read_b128 v[100:103], v0 offset:23072
	ds_read_b128 v[140:143], v80 offset:4608
	ds_read_b128 v[104:107], v80 offset:4640
	ds_read_b128 v[72:75], v0 offset:18496
	ds_read_b128 v[76:79], v80 offset:64
	ds_read_b128 v[82:85], v80 offset:96
	ds_read_b128 v[86:89], v0 offset:18528
	s_waitcnt lgkmcnt(10)
	v_mfma_f32_32x32x16_bf16 v[50:65], v[136:139], v[144:147], v[50:65]
	s_waitcnt lgkmcnt(7)
	v_mfma_f32_32x32x16_bf16 v[34:49], v[96:99], v[144:147], v[34:49]
	s_waitcnt lgkmcnt(5)
	v_mfma_f32_32x32x16_bf16 v[18:33], v[136:139], v[140:143], v[18:33]
	v_mfma_f32_32x32x16_bf16 v[2:17], v[96:99], v[140:143], v[2:17]
	v_mfma_f32_32x32x16_bf16 v[50:65], v[152:155], v[148:151], v[50:65]
	v_mfma_f32_32x32x16_bf16 v[34:49], v[100:103], v[148:151], v[34:49]
	s_waitcnt lgkmcnt(4)
	v_mfma_f32_32x32x16_bf16 v[18:33], v[152:155], v[104:107], v[18:33]
	v_mfma_f32_32x32x16_bf16 v[2:17], v[100:103], v[104:107], v[2:17]
	s_waitcnt lgkmcnt(0)
	ds_read_b128 v[96:99], v0 offset:23104
	ds_read_b128 v[100:103], v0 offset:23136
	v_mov_b32_e32 v0, v196
	s_waitcnt lgkmcnt(4)
	v_mfma_f32_32x32x16_bf16 v[50:65], v[72:75], v[76:79], v[50:65]
	s_waitcnt lgkmcnt(1)
	v_mfma_f32_32x32x16_bf16 v[34:49], v[96:99], v[76:79], v[34:49]
	ds_read_b128 v[76:79], v80 offset:4672
	ds_read_b128 v[104:107], v80 offset:4704
	s_waitcnt lgkmcnt(0)
	s_barrier
	s_barrier
	v_mfma_f32_32x32x16_bf16 v[18:33], v[72:75], v[76:79], v[18:33]
	s_nop 0
	v_and_b32_e32 v72, 31, v0
	v_ashrrev_i32_e32 v73, 1, v0
	v_mfma_f32_32x32x16_bf16 v[2:17], v[96:99], v[76:79], v[2:17]
	v_mfma_f32_32x32x16_bf16 v[50:65], v[86:89], v[82:85], v[50:65]
	v_mfma_f32_32x32x16_bf16 v[34:49], v[100:103], v[82:85], v[34:49]
	v_mfma_f32_32x32x16_bf16 v[18:33], v[86:89], v[104:107], v[18:33]
	v_and_or_b32 v86, v73, s1, v72
	v_cndmask_b32_e64 v72, 0, 1, s[8:9]
	v_cmp_ne_u32_e64 s[42:43], 1, v72
	v_mfma_f32_32x32x16_bf16 v[2:17], v[100:103], v[104:107], v[2:17]
	s_cbranch_vccnz .LBB0_1536
	v_lshl_add_u32 v72, v86, 2, v203
	ds_read_b32 v74, v72
	s_branch .LBB0_1537

; #define MFMA(a, b, c) __builtin_amdgcn_mfma_f32_32x32x16_bf16((a), (b), (c), 0, 0, 0)
; template <bool SWAP, int MI>
; DI void gemm_main(const bf16_t* __restrict__ A, int lda, const bf16_t* __restrict__ B, int ldb, int K, char* smem, f32x16 (&acc)[MI][2]) {
;     ...
;     for (int k0 = 0; k0 < K; k0 += 64) {
;         const bool more = (k0 + 64) < K;
;         if (more) {
; #pragma unroll
;             for (int i = 0; i < 2 * MI; ++i) ra[i] = *(const u32x4*)(ap + (size_t)(32 * i) * lda + k0 + 64);
; #pragma unroll
;             for (int i = 0; i < 4; ++i) rb[i] = *(const u32x4*)(bp + (size_t)(32 * i) * ldb + k0 + 64);
;         }
; #pragma unroll
;         for (int s = 0; s < 4; ++s) {
;             bf16x8 af[MI], bfr[2];
; #pragma unroll
;             for (int i = 0; i < MI; ++i) af[i] = *(const bf16x8*)(sA + (wm * (MI * 32) + i * 32 + l31) * GLD + s * 16 + h * 8);
; #pragma unroll
;             for (int j = 0; j < 2; ++j) bfr[j] = *(const bf16x8*)(sB + (wn * 64 + j * 32 + l31) * GLD + s * 16 + h * 8);
; #pragma unroll
;             for (int i = 0; i < MI; ++i)
; #pragma unroll
;                 for (int j = 0; j < 2; ++j) {
;                     if (SWAP) acc[i][j] = MFMA(bfr[j], af[i], acc[i][j]);
;                     else acc[i][j] = MFMA(af[i], bfr[j], acc[i][j]);
;                 }
;         }
;         __syncthreads();
;         if (more) {
; #pragma unroll
;             for (int i = 0; i < 2 * MI; ++i) *(u32x4*)(sA + (lr + 32 * i) * GLD + lc) = ra[i];
; #pragma unroll
;             for (int i = 0; i < 4; ++i) *(u32x4*)(sB + (lr + 32 * i) * GLD + lc) = rb[i];
;         }
;         __syncthreads();
.LBB0_1514:
	v_lshl_add_u64 v[64:65], v[58:59], 0, v[0:1]
	s_waitcnt vmcnt(4)
	v_add_co_u32_e32 v38, vcc, s31, v64
	v_lshl_add_u64 v[62:63], v[60:61], 0, v[0:1]
	s_nop 0
	v_addc_co_u32_e32 v39, vcc, 0, v65, vcc
	s_waitcnt vmcnt(2)
	v_add_co_u32_e32 v46, vcc, s31, v62
	ds_read_b128 v[76:79], v74 offset:9216
	s_nop 0
	v_addc_co_u32_e32 v47, vcc, 0, v63, vcc
	s_waitcnt vmcnt(1)
	v_add_co_u32_e32 v50, vcc, s67, v62
	global_load_dwordx4 v[34:37], v[64:65], off offset:128
	s_nop 0
	v_addc_co_u32_e32 v51, vcc, 0, v63, vcc
	s_waitcnt vmcnt(1)
	v_add_co_u32_e32 v54, vcc, s34, v62
	global_load_dwordx4 v[38:41], v[38:39], off offset:128
	s_nop 0
	global_load_dwordx4 v[42:45], v[62:63], off offset:128
	v_addc_co_u32_e32 v55, vcc, 0, v63, vcc
	global_load_dwordx4 v[46:49], v[46:47], off offset:128
	s_nop 0
	global_load_dwordx4 v[50:53], v[50:51], off offset:128
	ds_read_b128 v[80:83], v73
	global_load_dwordx4 v[54:57], v[54:55], off offset:128
	s_waitcnt lgkmcnt(0)
	v_mfma_f32_32x32x16_bf16 v[18:33], v[76:79], v[80:83], v[18:33]
	ds_read_b128 v[76:79], v74 offset:13824
	s_cmpk_lt_u32 s18, 0x7c0
	s_cselect_b64 s[46:47], -1, 0
	s_cmpk_gt_u32 s18, 0x7bf
	s_cselect_b64 s[44:45], -1, 0
	s_and_b64 vcc, exec, s[44:45]
	s_waitcnt lgkmcnt(0)
	v_mfma_f32_32x32x16_bf16 v[2:17], v[76:79], v[80:83], v[2:17]
	ds_read_b128 v[144:147], v74 offset:9248
	ds_read_b128 v[148:151], v73 offset:32
	ds_read_b128 v[140:143], v74 offset:13856
	ds_read_b128 v[136:139], v74 offset:9280
	ds_read_b128 v[80:83], v73 offset:64
	ds_read_b128 v[76:79], v74 offset:13888
	s_waitcnt lgkmcnt(4)
	v_mfma_f32_32x32x16_bf16 v[18:33], v[144:147], v[148:151], v[18:33]
	s_waitcnt lgkmcnt(3)
	v_mfma_f32_32x32x16_bf16 v[2:17], v[140:143], v[148:151], v[2:17]
	s_waitcnt lgkmcnt(1)
	v_mfma_f32_32x32x16_bf16 v[18:33], v[136:139], v[80:83], v[18:33]
	s_waitcnt lgkmcnt(0)
	v_mfma_f32_32x32x16_bf16 v[2:17], v[76:79], v[80:83], v[2:17]
	ds_read_b128 v[76:79], v74 offset:9312
	ds_read_b128 v[80:83], v73 offset:96
	ds_read_b128 v[84:87], v74 offset:13920
	s_waitcnt lgkmcnt(0)
	s_barrier
	s_waitcnt vmcnt(5)
	ds_write_b128 v72, v[34:37]
	s_waitcnt vmcnt(3)
	ds_write_b128 v72, v[42:45] offset:9216
	ds_write_b128 v72, v[38:41] offset:4608
	s_waitcnt vmcnt(2)
	ds_write_b128 v72, v[46:49] offset:13824
	s_waitcnt vmcnt(1)
	ds_write_b128 v72, v[50:53] offset:18432
	s_waitcnt vmcnt(0)
	ds_write_b128 v72, v[54:57] offset:23040
	v_mfma_f32_32x32x16_bf16 v[18:33], v[76:79], v[80:83], v[18:33]
	s_waitcnt lgkmcnt(0)
	s_barrier
	v_mfma_f32_32x32x16_bf16 v[2:17], v[84:87], v[80:83], v[2:17]
	s_cbranch_vccnz .LBB0_1516
	v_add_co_u32_e32 v38, vcc, 0x20000, v64
	global_load_dwordx4 v[34:37], v[64:65], off offset:256
	s_nop 0
	v_addc_co_u32_e32 v39, vcc, 0, v65, vcc
	v_add_co_u32_e32 v46, vcc, 0x20000, v62
	global_load_dwordx4 v[38:41], v[38:39], off offset:256
	s_nop 0
	global_load_dwordx4 v[42:45], v[62:63], off offset:256
	v_addc_co_u32_e32 v47, vcc, 0, v63, vcc
	v_add_co_u32_e32 v50, vcc, 0x40000, v62
	s_nop 1
	v_addc_co_u32_e32 v51, vcc, 0, v63, vcc
	v_add_co_u32_e32 v54, vcc, 0x60000, v62
	global_load_dwordx4 v[46:49], v[46:47], off offset:256
	s_nop 0
	global_load_dwordx4 v[50:53], v[50:51], off offset:256
	v_addc_co_u32_e32 v55, vcc, 0, v63, vcc
	global_load_dwordx4 v[54:57], v[54:55], off offset:256

; #define MFMA(a, b, c) __builtin_amdgcn_mfma_f32_32x32x16_bf16((a), (b), (c), 0, 0, 0)
; template <bool SWAP, int MI>
; DI void gemm_main(const bf16_t* __restrict__ A, int lda, const bf16_t* __restrict__ B, int ldb, int K, char* smem, f32x16 (&acc)[MI][2]) {
;     ...
;     const int lr = tid >> 3, lc = (tid & 7) * 8;
;     const bf16_t* ap = A + (size_t)lr * lda + lc;
;     const bf16_t* bp = B + (size_t)lr * ldb + lc;
; #pragma unroll
;     for (int i = 0; i < 2 * MI; ++i) ra[i] = *(const u32x4*)(ap + (size_t)(32 * i) * lda);
; #pragma unroll
;     for (int i = 0; i < 4; ++i) rb[i] = *(const u32x4*)(bp + (size_t)(32 * i) * ldb);
;     __syncthreads();
; #pragma unroll
;     for (int i = 0; i < 2 * MI; ++i) *(u32x4*)(sA + (lr + 32 * i) * GLD + lc) = ra[i];
; #pragma unroll
;     for (int i = 0; i < 4; ++i) *(u32x4*)(sB + (lr + 32 * i) * GLD + lc) = rb[i];
;     __syncthreads();
;     for (int k0 = 0; k0 < K; k0 += 64) {
;         const bool more = (k0 + 64) < K;
;         if (more) {
; #pragma unroll
;             for (int i = 0; i < 2 * MI; ++i) ra[i] = *(const u32x4*)(ap + (size_t)(32 * i) * lda + k0 + 64);
; #pragma unroll
;             for (int i = 0; i < 4; ++i) rb[i] = *(const u32x4*)(bp + (size_t)(32 * i) * ldb + k0 + 64);
;         }
; #pragma unroll
;         for (int s = 0; s < 4; ++s) {
;             bf16x8 af[MI], bfr[2];
; #pragma unroll
;             for (int i = 0; i < MI; ++i) af[i] = *(const bf16x8*)(sA + (wm * (MI * 32) + i * 32 + l31) * GLD + s * 16 + h * 8);
; #pragma unroll
;             for (int j = 0; j < 2; ++j) bfr[j] = *(const bf16x8*)(sB + (wn * 64 + j * 32 + l31) * GLD + s * 16 + h * 8);
; #pragma unroll
;             for (int i = 0; i < MI; ++i)
; #pragma unroll
;                 for (int j = 0; j < 2; ++j) {
;                     if (SWAP) acc[i][j] = MFMA(bfr[j], af[i], acc[i][j]);
;                     else acc[i][j] = MFMA(af[i], bfr[j], acc[i][j]);
;                 }
;         }
;         __syncthreads();
;         if (more) {
; #pragma unroll
;             for (int i = 0; i < 2 * MI; ++i) *(u32x4*)(sA + (lr + 32 * i) * GLD + lc) = ra[i];
; #pragma unroll
;             for (int i = 0; i < 4; ++i) *(u32x4*)(sB + (lr + 32 * i) * GLD + lc) = rb[i];
;         }
;         __syncthreads();
; DI void phase_cp(const Params& p, int l, char* smem) {
;     ...
;             __threadfence();
;             __syncthreads();
;             if (kv == 0) {
.LBB0_1518:
	s_and_b64 s[14:15], s[14:15], exec
	s_mov_b32 s1, 0x6108000
	s_cselect_b32 s1, s1, 0x6128000
	s_add_u32 s14, s57, s1
	s_addc_u32 s15, s63, 0
	s_mov_b64 s[16:17], -1
	s_and_b64 vcc, exec, s[12:13]
	buffer_wbl2 sc1
	s_waitcnt vmcnt(0)
	buffer_inv sc1
	s_barrier
	s_cbranch_vccz .LBB0_1522
	v_mov_b32_e32 v29, v196
	s_lshl_b64 s[10:11], s[10:11], 9
	s_add_u32 s10, s8, s10
	v_ashrrev_i32_e32 v26, 3, v29
	v_ashrrev_i32_e32 v27, 31, v26
	s_addc_u32 s11, s9, s11
	v_lshlrev_b64 v[2:3], 9, v[26:27]
	v_lshlrev_b32_e32 v0, 4, v29
	v_lshl_add_u64 v[4:5], s[10:11], 0, v[2:3]
	v_and_b32_e32 v0, 0x70, v0
	v_lshl_add_u64 v[34:35], v[4:5], 0, v[0:1]
	v_lshl_add_u64 v[10:11], s[14:15], 0, v[2:3]
	v_add_co_u32_e32 v36, vcc, s52, v34
	v_lshl_add_u64 v[40:41], v[10:11], 0, v[0:1]
	s_nop 0
	v_addc_co_u32_e32 v37, vcc, 0, v35, vcc
	v_add_co_u32_e32 v42, vcc, s52, v40
	s_mov_b32 s1, 0xc000
	s_nop 0
	v_addc_co_u32_e32 v43, vcc, 0, v41, vcc
	v_add_co_u32_e32 v44, vcc, s24, v40
	global_load_dwordx4 v[2:5], v[34:35], off
	global_load_dwordx4 v[6:9], v[36:37], off
	v_addc_co_u32_e32 v45, vcc, 0, v41, vcc
	v_add_co_u32_e32 v84, vcc, s1, v40
	global_load_dwordx4 v[10:13], v[40:41], off
	global_load_dwordx4 v[14:17], v[42:43], off
	v_addc_co_u32_e32 v85, vcc, 0, v41, vcc
	global_load_dwordx4 v[18:21], v[44:45], off
	global_load_dwordx4 v[22:25], v[84:85], off
	v_and_b32_e32 v27, 31, v29
	v_lshrrev_b32_e32 v28, 2, v29
	v_lshrrev_b32_e32 v30, 1, v29
	v_and_or_b32 v27, v28, s53, v27
	v_and_b32_e32 v28, 16, v30
	v_mad_u64_u32 v[86:87], s[10:11], v26, s35, v[0:1]
	v_mad_u64_u32 v[38:39], s[10:11], v27, s35, v[28:29]
	s_barrier
	v_and_b32_e32 v0, 0x5f, v29
	v_mad_u32_u24 v0, v0, s35, v28
	s_waitcnt vmcnt(5)
	ds_write_b128 v86, v[2:5]
	s_waitcnt vmcnt(3)
	ds_write_b128 v86, v[10:13] offset:9216
	ds_write_b128 v86, v[6:9] offset:4608
	s_waitcnt vmcnt(2)
	ds_write_b128 v86, v[14:17] offset:13824
	s_waitcnt vmcnt(1)
	ds_write_b128 v86, v[18:21] offset:18432
	s_waitcnt vmcnt(0)
	ds_write_b128 v86, v[22:25] offset:23040
	s_waitcnt lgkmcnt(0)
	s_barrier
	ds_read_b128 v[2:5], v38
	ds_read_b128 v[6:9], v0 offset:9216
	ds_read_b128 v[46:49], v38 offset:32
	ds_read_b128 v[50:53], v0 offset:9248
	s_waitcnt lgkmcnt(2)
	v_mfma_f32_32x32x16_bf16 v[18:33], v[2:5], v[6:9], 0
	ds_read_b128 v[6:9], v0 offset:13824
	ds_read_b128 v[54:57], v0 offset:13856
	s_waitcnt lgkmcnt(1)
	v_mfma_f32_32x32x16_bf16 v[2:17], v[2:5], v[6:9], 0
	v_mfma_f32_32x32x16_bf16 v[18:33], v[46:49], v[50:53], v[18:33]
	s_waitcnt lgkmcnt(0)
	v_mfma_f32_32x32x16_bf16 v[2:17], v[46:49], v[54:57], v[2:17]
	ds_read_b128 v[46:49], v38 offset:64
	ds_read_b128 v[50:53], v0 offset:9280
	ds_read_b128 v[54:57], v38 offset:96
	ds_read_b128 v[58:61], v0 offset:9312
	s_waitcnt lgkmcnt(2)
	v_mfma_f32_32x32x16_bf16 v[18:33], v[46:49], v[50:53], v[18:33]
	ds_read_b128 v[50:53], v0 offset:13888
	ds_read_b128 v[62:65], v0 offset:13920
	s_waitcnt lgkmcnt(1)
	v_mfma_f32_32x32x16_bf16 v[2:17], v[46:49], v[50:53], v[2:17]
	global_load_dwordx4 v[46:49], v[34:35], off offset:128
	global_load_dwordx4 v[50:53], v[36:37], off offset:128
	global_load_dwordx4 v[72:75], v[40:41], off offset:128
	global_load_dwordx4 v[76:79], v[42:43], off offset:128
	v_mfma_f32_32x32x16_bf16 v[18:33], v[54:57], v[58:61], v[18:33]
	global_load_dwordx4 v[58:61], v[44:45], off offset:128
	global_load_dwordx4 v[80:83], v[84:85], off offset:128
	s_waitcnt lgkmcnt(0)
	s_barrier
	s_waitcnt vmcnt(5)
	ds_write_b128 v86, v[46:49]
	s_waitcnt vmcnt(4)
	ds_write_b128 v86, v[50:53] offset:4608
	s_waitcnt vmcnt(3)
	ds_write_b128 v86, v[72:75] offset:9216
	s_waitcnt vmcnt(2)
	ds_write_b128 v86, v[76:79] offset:13824
	s_waitcnt vmcnt(1)
	ds_write_b128 v86, v[58:61] offset:18432
	s_waitcnt vmcnt(0)
	ds_write_b128 v86, v[80:83] offset:23040
	v_mfma_f32_32x32x16_bf16 v[2:17], v[54:57], v[62:65], v[2:17]
	s_waitcnt lgkmcnt(0)
	s_barrier
	ds_read_b128 v[136:139], v38
	ds_read_b128 v[148:151], v0 offset:9216
	ds_read_b128 v[152:155], v38 offset:32
	ds_read_b128 v[156:159], v0 offset:9248
	ds_read_b128 v[144:147], v0 offset:13824
	ds_read_b128 v[160:163], v0 offset:13856
	ds_read_b128 v[46:49], v38 offset:64
	ds_read_b128 v[140:143], v0 offset:9280
	ds_read_b128 v[54:57], v38 offset:96
	ds_read_b128 v[58:61], v0 offset:9312
	ds_read_b128 v[50:53], v0 offset:13888
	ds_read_b128 v[62:65], v0 offset:13920
	s_waitcnt lgkmcnt(10)
	v_mfma_f32_32x32x16_bf16 v[18:33], v[136:139], v[148:151], v[18:33]
	s_waitcnt lgkmcnt(7)
	v_mfma_f32_32x32x16_bf16 v[2:17], v[136:139], v[144:147], v[2:17]
	v_mfma_f32_32x32x16_bf16 v[18:33], v[152:155], v[156:159], v[18:33]
	s_waitcnt lgkmcnt(6)
	v_mfma_f32_32x32x16_bf16 v[2:17], v[152:155], v[160:163], v[2:17]
	s_waitcnt lgkmcnt(4)
	v_mfma_f32_32x32x16_bf16 v[18:33], v[46:49], v[140:143], v[18:33]
	s_waitcnt lgkmcnt(1)
	v_mfma_f32_32x32x16_bf16 v[2:17], v[46:49], v[50:53], v[2:17]
	s_waitcnt lgkmcnt(0)
	global_load_dwordx4 v[46:49], v[34:35], off offset:256
	global_load_dwordx4 v[50:53], v[36:37], off offset:256
	global_load_dwordx4 v[72:75], v[40:41], off offset:256
	global_load_dwordx4 v[76:79], v[42:43], off offset:256
	v_mfma_f32_32x32x16_bf16 v[18:33], v[54:57], v[58:61], v[18:33]
	global_load_dwordx4 v[58:61], v[44:45], off offset:256
	global_load_dwordx4 v[80:83], v[84:85], off offset:256
	s_waitcnt lgkmcnt(0)
	s_barrier
; template <bool SWAP, int MI>
; DI void gemm_main(const bf16_t* __restrict__ A, int lda, const bf16_t* __restrict__ B, int ldb, int K, char* smem, f32x16 (&acc)[MI][2]) {
;     ...
;     for (int k0 = 0; k0 < K; k0 += 64) {
;         const bool more = (k0 + 64) < K;
;         if (more) {
; #pragma unroll
;             for (int i = 0; i < 2 * MI; ++i) ra[i] = *(const u32x4*)(ap + (size_t)(32 * i) * lda + k0 + 64);
; #pragma unroll
;             for (int i = 0; i < 4; ++i) rb[i] = *(const u32x4*)(bp + (size_t)(32 * i) * ldb + k0 + 64);
;         }
; #pragma unroll
;         for (int s = 0; s < 4; ++s) {
;             bf16x8 af[MI], bfr[2];
; #pragma unroll
;             for (int i = 0; i < MI; ++i) af[i] = *(const bf16x8*)(sA + (wm * (MI * 32) + i * 32 + l31) * GLD + s * 16 + h * 8);
; #pragma unroll
;             for (int j = 0; j < 2; ++j) bfr[j] = *(const bf16x8*)(sB + (wn * 64 + j * 32 + l31) * GLD + s * 16 + h * 8);
; #pragma unroll
;             for (int i = 0; i < MI; ++i)
; #pragma unroll
;                 for (int j = 0; j < 2; ++j) {
;                     if (SWAP) acc[i][j] = MFMA(bfr[j], af[i], acc[i][j]);
;                     else acc[i][j] = MFMA(af[i], bfr[j], acc[i][j]);
;                 }
;         }
;         __syncthreads();
;         if (more) {
; #pragma unroll
;             for (int i = 0; i < 2 * MI; ++i) *(u32x4*)(sA + (lr + 32 * i) * GLD + lc) = ra[i];
; #pragma unroll
;             for (int i = 0; i < 4; ++i) *(u32x4*)(sB + (lr + 32 * i) * GLD + lc) = rb[i];
;         }
;         __syncthreads();
; DI void phase_cp(const Params& p, int l, char* smem) {
;     ...
;                 gemm_main<false, 1>(hid + (size_t)m0 * 256, 256, w2, 256, 256, smem, acc1);
;                 if (wn == 0) {
;                     bf16_t* vct = (bf16_t*)(ws + OFF_VCT);
; #pragma unroll
;                     for (int j = 0; j < 2; ++j) {
;                         const int dv = j * 32 + l31;
; #pragma unroll
;                             for (int g = 0; g < 4; ++g) {
;                                 const int m = m0 + wm * 32 + 8 * g + 4 * h;
;                                 const int bg = m >> 9, n = m & 511;
;                                 uint2 o;
;                                 o.x = pack2(acc1[0][j][4 * g], acc1[0][j][4 * g + 1]);
;                                 o.y = pack2(acc1[0][j][4 * g + 2], acc1[0][j][4 * g + 3]);
	s_waitcnt vmcnt(5)
	ds_write_b128 v86, v[46:49]
	s_waitcnt vmcnt(4)
	ds_write_b128 v86, v[50:53] offset:4608
	s_waitcnt vmcnt(3)
	ds_write_b128 v86, v[72:75] offset:9216
	s_waitcnt vmcnt(2)
	ds_write_b128 v86, v[76:79] offset:13824
	s_waitcnt vmcnt(1)
	ds_write_b128 v86, v[58:61] offset:18432
	s_waitcnt vmcnt(0)
	ds_write_b128 v86, v[80:83] offset:23040
	v_mfma_f32_32x32x16_bf16 v[2:17], v[54:57], v[62:65], v[2:17]
	s_waitcnt lgkmcnt(0)
	s_barrier
	ds_read_b128 v[136:139], v38
	ds_read_b128 v[148:151], v0 offset:9216
	ds_read_b128 v[152:155], v38 offset:32
	ds_read_b128 v[156:159], v0 offset:9248
	ds_read_b128 v[144:147], v0 offset:13824
	ds_read_b128 v[160:163], v0 offset:13856
	ds_read_b128 v[46:49], v38 offset:64
	ds_read_b128 v[140:143], v0 offset:9280
	ds_read_b128 v[54:57], v38 offset:96
	ds_read_b128 v[58:61], v0 offset:9312
	ds_read_b128 v[50:53], v0 offset:13888
	ds_read_b128 v[62:65], v0 offset:13920
	s_waitcnt lgkmcnt(10)
	v_mfma_f32_32x32x16_bf16 v[18:33], v[136:139], v[148:151], v[18:33]
	s_waitcnt lgkmcnt(7)
	v_mfma_f32_32x32x16_bf16 v[2:17], v[136:139], v[144:147], v[2:17]
	v_mfma_f32_32x32x16_bf16 v[18:33], v[152:155], v[156:159], v[18:33]
	s_waitcnt lgkmcnt(6)
	v_mfma_f32_32x32x16_bf16 v[2:17], v[152:155], v[160:163], v[2:17]
	s_waitcnt lgkmcnt(4)
	v_mfma_f32_32x32x16_bf16 v[18:33], v[46:49], v[140:143], v[18:33]
	s_waitcnt lgkmcnt(1)
	v_mfma_f32_32x32x16_bf16 v[2:17], v[46:49], v[50:53], v[2:17]
	s_waitcnt lgkmcnt(0)
	global_load_dwordx4 v[46:49], v[34:35], off offset:384
	s_nop 0
	global_load_dwordx4 v[34:37], v[36:37], off offset:384
	s_nop 0
	global_load_dwordx4 v[50:53], v[40:41], off offset:384
	s_nop 0
	global_load_dwordx4 v[40:43], v[42:43], off offset:384
	v_mfma_f32_32x32x16_bf16 v[18:33], v[54:57], v[58:61], v[18:33]
	global_load_dwordx4 v[58:61], v[44:45], off offset:384
	global_load_dwordx4 v[72:75], v[84:85], off offset:384
	s_waitcnt lgkmcnt(0)
	s_barrier
	s_waitcnt vmcnt(5)
	ds_write_b128 v86, v[46:49]
	s_waitcnt vmcnt(4)
	ds_write_b128 v86, v[34:37] offset:4608
	s_waitcnt vmcnt(3)
	ds_write_b128 v86, v[50:53] offset:9216
	s_waitcnt vmcnt(2)
	ds_write_b128 v86, v[40:43] offset:13824
	s_waitcnt vmcnt(1)
	ds_write_b128 v86, v[58:61] offset:18432
	s_waitcnt vmcnt(0)
	ds_write_b128 v86, v[72:75] offset:23040
	v_mfma_f32_32x32x16_bf16 v[2:17], v[54:57], v[62:65], v[2:17]
	s_waitcnt lgkmcnt(0)
	s_barrier
	ds_read_b128 v[136:139], v38
	ds_read_b128 v[144:147], v0 offset:9216
	ds_read_b128 v[148:151], v38 offset:32
	ds_read_b128 v[152:155], v0 offset:9248
	ds_read_b128 v[140:143], v0 offset:13824
	ds_read_b128 v[52:55], v0 offset:13856
	ds_read_b128 v[34:37], v38 offset:64
	ds_read_b128 v[40:43], v0 offset:9280
	ds_read_b128 v[44:47], v38 offset:96
	ds_read_b128 v[48:51], v0 offset:9312
	s_waitcnt lgkmcnt(8)
	v_mfma_f32_32x32x16_bf16 v[18:33], v[136:139], v[144:147], v[18:33]
	s_waitcnt lgkmcnt(5)
	v_mfma_f32_32x32x16_bf16 v[2:17], v[136:139], v[140:143], v[2:17]
	v_mfma_f32_32x32x16_bf16 v[18:33], v[148:151], v[152:155], v[18:33]
	s_waitcnt lgkmcnt(4)
	v_mfma_f32_32x32x16_bf16 v[2:17], v[148:151], v[52:55], v[2:17]
	s_waitcnt lgkmcnt(2)
	v_mfma_f32_32x32x16_bf16 v[18:33], v[34:37], v[40:43], v[18:33]
	s_waitcnt lgkmcnt(0)
	ds_read_b128 v[38:41], v0 offset:13888
	ds_read_b128 v[52:55], v0 offset:13920
	s_waitcnt lgkmcnt(0)
	s_barrier
	s_barrier
	v_mfma_f32_32x32x16_bf16 v[2:17], v[34:37], v[38:41], v[2:17]
	v_mfma_f32_32x32x16_bf16 v[18:33], v[44:47], v[48:51], v[18:33]
	v_mfma_f32_32x32x16_bf16 v[2:17], v[44:47], v[52:55], v[2:17]
	s_and_saveexec_b64 s[10:11], s[38:39]
	s_cbranch_execz .LBB0_1521
	s_and_b32 s1, s72, 0x7fffffe
	v_add_u32_e32 v0, s1, v92
	v_lshlrev_b32_e32 v35, 5, v0
	v_bfe_i32 v34, v0, 4, 23
	s_movk_i32 s1, 0x1e0
	v_and_or_b32 v0, v35, s1, v66
	v_ashrrev_i32_e32 v35, 31, v34
	v_lshlrev_b64 v[34:35], 16, v[34:35]
	v_lshl_add_u64 v[34:35], v[70:71], 0, v[34:35]
	v_lshlrev_b32_e32 v0, 1, v0
	v_cvt_pk_bf16_f32 v18, v18, v19
	v_cvt_pk_bf16_f32 v19, v20, v21
	v_lshl_add_u64 v[20:21], v[34:35], 0, v[0:1]
	global_store_dwordx2 v[20:21], v[18:19], off
	v_cvt_pk_bf16_f32 v18, v22, v23
	v_cvt_pk_bf16_f32 v19, v24, v25
	global_store_dwordx2 v[20:21], v[18:19], off offset:16
	v_cvt_pk_bf16_f32 v18, v26, v27
	v_cvt_pk_bf16_f32 v19, v28, v29
	global_store_dwordx2 v[20:21], v[18:19], off offset:32
	v_cvt_pk_bf16_f32 v18, v30, v31
	v_cvt_pk_bf16_f32 v19, v32, v33
	s_mov_b64 s[12:13], 0x8000
	global_store_dwordx2 v[20:21], v[18:19], off offset:48
	v_lshl_add_u64 v[18:19], v[34:35], 0, s[12:13]
	v_cvt_pk_bf16_f32 v2, v2, v3
	v_cvt_pk_bf16_f32 v3, v4, v5
	v_lshl_add_u64 v[4:5], v[18:19], 0, v[0:1]
	global_store_dwordx2 v[4:5], v[2:3], off
	v_or_b32_e32 v4, 16, v0
	v_mov_b32_e32 v5, v1
	v_cvt_pk_bf16_f32 v2, v6, v7
	v_cvt_pk_bf16_f32 v3, v8, v9
	v_lshl_add_u64 v[4:5], v[18:19], 0, v[4:5]
	global_store_dwordx2 v[4:5], v[2:3], off
	v_or_b32_e32 v4, 32, v0
	v_mov_b32_e32 v5, v1
	v_cvt_pk_bf16_f32 v2, v10, v11
	v_cvt_pk_bf16_f32 v3, v12, v13
	v_lshl_add_u64 v[4:5], v[18:19], 0, v[4:5]
	v_or_b32_e32 v0, 48, v0
	global_store_dwordx2 v[4:5], v[2:3], off
	v_cvt_pk_bf16_f32 v2, v14, v15
	v_cvt_pk_bf16_f32 v3, v16, v17
	v_lshl_add_u64 v[4:5], v[18:19], 0, v[0:1]
	global_store_dwordx2 v[4:5], v[2:3], off

; template <bool SWAP, int MI>
; DI void gemm_main(const bf16_t* __restrict__ A, int lda, const bf16_t* __restrict__ B, int ldb, int K, char* smem, f32x16 (&acc)[MI][2]) {
;     ...
;     const int lr = tid >> 3, lc = (tid & 7) * 8;
;     const bf16_t* ap = A + (size_t)lr * lda + lc;
;     const bf16_t* bp = B + (size_t)lr * ldb + lc;
; #pragma unroll
;     for (int i = 0; i < 2 * MI; ++i) ra[i] = *(const u32x4*)(ap + (size_t)(32 * i) * lda);
; #pragma unroll
;     for (int i = 0; i < 4; ++i) rb[i] = *(const u32x4*)(bp + (size_t)(32 * i) * ldb);
;     __syncthreads();
; #pragma unroll
;     for (int i = 0; i < 2 * MI; ++i) *(u32x4*)(sA + (lr + 32 * i) * GLD + lc) = ra[i];
; #pragma unroll
;     for (int i = 0; i < 4; ++i) *(u32x4*)(sB + (lr + 32 * i) * GLD + lc) = rb[i];
;     __syncthreads();
;     for (int k0 = 0; k0 < K; k0 += 64) {
;         const bool more = (k0 + 64) < K;
;         if (more) {
; #pragma unroll
;             for (int i = 0; i < 2 * MI; ++i) ra[i] = *(const u32x4*)(ap + (size_t)(32 * i) * lda + k0 + 64);
; #pragma unroll
;             for (int i = 0; i < 4; ++i) rb[i] = *(const u32x4*)(bp + (size_t)(32 * i) * ldb + k0 + 64);
;         }
; #pragma unroll
;         for (int s = 0; s < 4; ++s) {
;             bf16x8 af[MI], bfr[2];
; #pragma unroll
;             for (int i = 0; i < MI; ++i) af[i] = *(const bf16x8*)(sA + (wm * (MI * 32) + i * 32 + l31) * GLD + s * 16 + h * 8);
; #pragma unroll
;             for (int j = 0; j < 2; ++j) bfr[j] = *(const bf16x8*)(sB + (wn * 64 + j * 32 + l31) * GLD + s * 16 + h * 8);
; #pragma unroll
;             for (int i = 0; i < MI; ++i)
; #pragma unroll
;                 for (int j = 0; j < 2; ++j) {
;                     if (SWAP) acc[i][j] = MFMA(bfr[j], af[i], acc[i][j]);
;                     else acc[i][j] = MFMA(af[i], bfr[j], acc[i][j]);
;                 }
;         }
;         __syncthreads();
;         if (more) {
; #pragma unroll
;             for (int i = 0; i < 2 * MI; ++i) *(u32x4*)(sA + (lr + 32 * i) * GLD + lc) = ra[i];
; #pragma unroll
;             for (int i = 0; i < 4; ++i) *(u32x4*)(sB + (lr + 32 * i) * GLD + lc) = rb[i];
;         }
;         __syncthreads();
; DI void phase_cp(const Params& p, int l, char* smem) {
;     ...
;             if (kv == 0) {
;                 gemm_main<true, 1>(hid + (size_t)m0 * 256, 256, w2, 256, 256, smem, acc1);
.LBB0_1522:
	s_andn2_b64 vcc, exec, s[16:17]
	s_cbranch_vccnz .LBB0_1471
	s_ashr_i32 s1, s0, 31
	s_nop 3
	v_mov_b32_e32 v28, v196
	s_lshl_b64 s[0:1], s[0:1], 9
	s_add_u32 s0, s8, s0
	v_ashrrev_i32_e32 v26, 3, v28
	v_ashrrev_i32_e32 v27, 31, v26
	s_addc_u32 s1, s9, s1
	v_lshlrev_b64 v[2:3], 9, v[26:27]
	v_lshlrev_b32_e32 v0, 4, v28
	v_lshl_add_u64 v[4:5], s[0:1], 0, v[2:3]
	v_and_b32_e32 v0, 0x70, v0
	v_lshl_add_u64 v[34:35], v[4:5], 0, v[0:1]
	v_lshl_add_u64 v[10:11], s[14:15], 0, v[2:3]
	v_add_co_u32_e32 v36, vcc, s52, v34
	v_lshl_add_u64 v[38:39], v[10:11], 0, v[0:1]
	s_nop 0
	v_addc_co_u32_e32 v37, vcc, 0, v35, vcc
	v_add_co_u32_e32 v40, vcc, s52, v38
	s_mov_b32 s0, 0xc000
	s_nop 0
	v_addc_co_u32_e32 v41, vcc, 0, v39, vcc
	v_add_co_u32_e32 v42, vcc, s24, v38
	global_load_dwordx4 v[2:5], v[34:35], off
	global_load_dwordx4 v[6:9], v[36:37], off
	v_addc_co_u32_e32 v43, vcc, 0, v39, vcc
	v_add_co_u32_e32 v44, vcc, s0, v38
	global_load_dwordx4 v[10:13], v[38:39], off
	global_load_dwordx4 v[14:17], v[40:41], off
	v_addc_co_u32_e32 v45, vcc, 0, v39, vcc
	global_load_dwordx4 v[18:21], v[42:43], off
	global_load_dwordx4 v[22:25], v[44:45], off
	v_lshrrev_b32_e32 v30, 1, v28
	v_and_b32_e32 v27, 31, v28
	v_lshrrev_b32_e32 v29, 2, v28
	v_and_b32_e32 v31, 0x5f, v28
	v_and_b32_e32 v28, 16, v30
	v_mad_u64_u32 v[46:47], s[0:1], v26, s35, v[0:1]
	v_mad_u32_u24 v0, v31, s35, v28
	s_barrier
	s_waitcnt vmcnt(5)
	ds_write_b128 v46, v[2:5]
	s_waitcnt vmcnt(3)
	ds_write_b128 v46, v[10:13] offset:9216
	ds_write_b128 v46, v[6:9] offset:4608
	s_waitcnt vmcnt(2)
	ds_write_b128 v46, v[14:17] offset:13824
	s_waitcnt vmcnt(1)
	ds_write_b128 v46, v[18:21] offset:18432
	s_waitcnt vmcnt(0)
	ds_write_b128 v46, v[22:25] offset:23040
	s_waitcnt lgkmcnt(0)
	s_barrier
	ds_read_b128 v[2:5], v0 offset:9216
	v_and_or_b32 v6, v29, s53, v27
	v_mad_u64_u32 v[48:49], s[0:1], v6, s35, v[28:29]
	ds_read_b128 v[6:9], v48
	ds_read_b128 v[50:53], v48 offset:32
	ds_read_b128 v[54:57], v0 offset:9248
	s_waitcnt lgkmcnt(2)
	v_mfma_f32_32x32x16_bf16 v[18:33], v[2:5], v[6:9], 0
	ds_read_b128 v[2:5], v0 offset:13824
	ds_read_b128 v[58:61], v0 offset:13856
	s_waitcnt lgkmcnt(1)
	v_mfma_f32_32x32x16_bf16 v[2:17], v[2:5], v[6:9], 0
	v_mfma_f32_32x32x16_bf16 v[18:33], v[54:57], v[50:53], v[18:33]
	s_waitcnt lgkmcnt(0)
	v_mfma_f32_32x32x16_bf16 v[2:17], v[58:61], v[50:53], v[2:17]
	ds_read_b128 v[50:53], v0 offset:9280
	ds_read_b128 v[54:57], v48 offset:64
	ds_read_b128 v[58:61], v48 offset:96
	ds_read_b128 v[62:65], v0 offset:9312
	s_waitcnt lgkmcnt(2)
	v_mfma_f32_32x32x16_bf16 v[18:33], v[50:53], v[54:57], v[18:33]
	ds_read_b128 v[50:53], v0 offset:13888
	ds_read_b128 v[72:75], v0 offset:13920
	s_waitcnt lgkmcnt(1)
	v_mfma_f32_32x32x16_bf16 v[2:17], v[50:53], v[54:57], v[2:17]
	global_load_dwordx4 v[50:53], v[34:35], off offset:128
	global_load_dwordx4 v[54:57], v[36:37], off offset:128
	global_load_dwordx4 v[76:79], v[38:39], off offset:128
	global_load_dwordx4 v[80:83], v[40:41], off offset:128
	v_mfma_f32_32x32x16_bf16 v[18:33], v[62:65], v[58:61], v[18:33]
	global_load_dwordx4 v[62:65], v[42:43], off offset:128
	global_load_dwordx4 v[84:87], v[44:45], off offset:128
	s_waitcnt lgkmcnt(0)
	s_barrier
	s_waitcnt vmcnt(5)
	ds_write_b128 v46, v[50:53]
	s_waitcnt vmcnt(4)
	ds_write_b128 v46, v[54:57] offset:4608
	s_waitcnt vmcnt(3)
	ds_write_b128 v46, v[76:79] offset:9216
	s_waitcnt vmcnt(2)
	ds_write_b128 v46, v[80:83] offset:13824
	s_waitcnt vmcnt(1)
	ds_write_b128 v46, v[62:65] offset:18432
	s_waitcnt vmcnt(0)
	ds_write_b128 v46, v[84:87] offset:23040
	v_mfma_f32_32x32x16_bf16 v[2:17], v[72:75], v[58:61], v[2:17]
	s_waitcnt lgkmcnt(0)
	s_barrier
	ds_read_b128 v[144:147], v0 offset:9216
	ds_read_b128 v[148:151], v48
	ds_read_b128 v[152:155], v48 offset:32
	ds_read_b128 v[156:159], v0 offset:9248
	ds_read_b128 v[140:143], v0 offset:13824
	ds_read_b128 v[160:163], v0 offset:13856
	ds_read_b128 v[136:139], v0 offset:9280
	ds_read_b128 v[54:57], v48 offset:64
	ds_read_b128 v[58:61], v48 offset:96
	ds_read_b128 v[62:65], v0 offset:9312
	ds_read_b128 v[50:53], v0 offset:13888
	ds_read_b128 v[72:75], v0 offset:13920
	s_waitcnt lgkmcnt(10)
	v_mfma_f32_32x32x16_bf16 v[18:33], v[144:147], v[148:151], v[18:33]
	s_waitcnt lgkmcnt(7)
	v_mfma_f32_32x32x16_bf16 v[2:17], v[140:143], v[148:151], v[2:17]
	v_mfma_f32_32x32x16_bf16 v[18:33], v[156:159], v[152:155], v[18:33]
	s_waitcnt lgkmcnt(6)
	v_mfma_f32_32x32x16_bf16 v[2:17], v[160:163], v[152:155], v[2:17]
	s_waitcnt lgkmcnt(4)
	v_mfma_f32_32x32x16_bf16 v[18:33], v[136:139], v[54:57], v[18:33]
	s_waitcnt lgkmcnt(1)
	v_mfma_f32_32x32x16_bf16 v[2:17], v[50:53], v[54:57], v[2:17]
	s_waitcnt lgkmcnt(0)
	global_load_dwordx4 v[50:53], v[34:35], off offset:256
	global_load_dwordx4 v[54:57], v[36:37], off offset:256
	global_load_dwordx4 v[76:79], v[38:39], off offset:256
	global_load_dwordx4 v[80:83], v[40:41], off offset:256
	v_mfma_f32_32x32x16_bf16 v[18:33], v[62:65], v[58:61], v[18:33]
	global_load_dwordx4 v[62:65], v[42:43], off offset:256
	global_load_dwordx4 v[84:87], v[44:45], off offset:256
	s_waitcnt lgkmcnt(0)
	s_barrier
; template <bool SWAP, int MI>
; DI void gemm_main(const bf16_t* __restrict__ A, int lda, const bf16_t* __restrict__ B, int ldb, int K, char* smem, f32x16 (&acc)[MI][2]) {
;     ...
; #pragma unroll
;         for (int s = 0; s < 4; ++s) {
;             bf16x8 af[MI], bfr[2];
; #pragma unroll
;             for (int i = 0; i < MI; ++i) af[i] = *(const bf16x8*)(sA + (wm * (MI * 32) + i * 32 + l31) * GLD + s * 16 + h * 8);
; #pragma unroll
;             for (int j = 0; j < 2; ++j) bfr[j] = *(const bf16x8*)(sB + (wn * 64 + j * 32 + l31) * GLD + s * 16 + h * 8);
; #pragma unroll
;             for (int i = 0; i < MI; ++i)
; #pragma unroll
;                 for (int j = 0; j < 2; ++j) {
;                     if (SWAP) acc[i][j] = MFMA(bfr[j], af[i], acc[i][j]);
;                     else acc[i][j] = MFMA(af[i], bfr[j], acc[i][j]);
;                 }
;         }
;         __syncthreads();
;         if (more) {
; #pragma unroll
;             for (int i = 0; i < 2 * MI; ++i) *(u32x4*)(sA + (lr + 32 * i) * GLD + lc) = ra[i];
; #pragma unroll
;             for (int i = 0; i < 4; ++i) *(u32x4*)(sB + (lr + 32 * i) * GLD + lc) = rb[i];
;         }
;         __syncthreads();
; DI void phase_cp(const Params& p, int l, char* smem) {
;     ...
;                 gemm_main<true, 1>(hid + (size_t)m0 * 256, 256, w2, 256, 256, smem, acc1);
;                 if (wn == 0) {
;                     bf16_t* kc = (bf16_t*)(ws + OFF_KC);
;                     {
;                         const int m = m0 + wm * 32 + l31;
;                         const int bg = m >> 9, n = m & 511, b = bg >> 1;
;                         const bool live = n < 511;
;                         const size_t tpos = (size_t)b * S_ + (live ? 16 * n + 31 : 0);
; #pragma unroll
;                         for (int j = 0; j < 2; ++j) {
;                             f32x16 v = acc1[0][j];
;                             if (j == 0) {
;                                 const float4 c = *(const float4*)(cs16 + tpos * 16 + 4 * h);
;                                 const float4 s = *(const float4*)(cs16 + tpos * 16 + 8 + 4 * h);
;                                 const float cc[4] = {c.x, c.y, c.z, c.w}, sn[4] = {s.x, s.y, s.z, s.w};
; #pragma unroll
;                                 for (int r = 0; r < 4; ++r) {
;                                     const float x1 = v[r], x2 = v[4 + r];
	s_waitcnt vmcnt(5)
	ds_write_b128 v46, v[50:53]
	s_waitcnt vmcnt(4)
	ds_write_b128 v46, v[54:57] offset:4608
	s_waitcnt vmcnt(3)
	ds_write_b128 v46, v[76:79] offset:9216
	s_waitcnt vmcnt(2)
	ds_write_b128 v46, v[80:83] offset:13824
	s_waitcnt vmcnt(1)
	ds_write_b128 v46, v[62:65] offset:18432
	s_waitcnt vmcnt(0)
	ds_write_b128 v46, v[84:87] offset:23040
	v_mfma_f32_32x32x16_bf16 v[2:17], v[72:75], v[58:61], v[2:17]
	s_waitcnt lgkmcnt(0)
	s_barrier
	ds_read_b128 v[144:147], v0 offset:9216
	ds_read_b128 v[148:151], v48
	ds_read_b128 v[152:155], v48 offset:32
	ds_read_b128 v[156:159], v0 offset:9248
	ds_read_b128 v[140:143], v0 offset:13824
	ds_read_b128 v[160:163], v0 offset:13856
	ds_read_b128 v[136:139], v0 offset:9280
	ds_read_b128 v[54:57], v48 offset:64
	ds_read_b128 v[58:61], v48 offset:96
	ds_read_b128 v[62:65], v0 offset:9312
	ds_read_b128 v[50:53], v0 offset:13888
	ds_read_b128 v[72:75], v0 offset:13920
	s_waitcnt lgkmcnt(10)
	v_mfma_f32_32x32x16_bf16 v[18:33], v[144:147], v[148:151], v[18:33]
	s_waitcnt lgkmcnt(7)
	v_mfma_f32_32x32x16_bf16 v[2:17], v[140:143], v[148:151], v[2:17]
	v_mfma_f32_32x32x16_bf16 v[18:33], v[156:159], v[152:155], v[18:33]
	s_waitcnt lgkmcnt(6)
	v_mfma_f32_32x32x16_bf16 v[2:17], v[160:163], v[152:155], v[2:17]
	s_waitcnt lgkmcnt(4)
	v_mfma_f32_32x32x16_bf16 v[18:33], v[136:139], v[54:57], v[18:33]
	s_waitcnt lgkmcnt(1)
	v_mfma_f32_32x32x16_bf16 v[2:17], v[50:53], v[54:57], v[2:17]
	s_waitcnt lgkmcnt(0)
	global_load_dwordx4 v[50:53], v[34:35], off offset:384
	s_nop 0
	global_load_dwordx4 v[34:37], v[36:37], off offset:384
	s_nop 0
	global_load_dwordx4 v[54:57], v[38:39], off offset:384
	s_nop 0
	global_load_dwordx4 v[38:41], v[40:41], off offset:384
	v_mfma_f32_32x32x16_bf16 v[18:33], v[62:65], v[58:61], v[18:33]
	global_load_dwordx4 v[62:65], v[42:43], off offset:384
	s_nop 0
	global_load_dwordx4 v[42:45], v[44:45], off offset:384
	s_waitcnt lgkmcnt(0)
	s_barrier
	s_waitcnt vmcnt(5)
	ds_write_b128 v46, v[50:53]
	s_waitcnt vmcnt(4)
	ds_write_b128 v46, v[34:37] offset:4608
	s_waitcnt vmcnt(3)
	ds_write_b128 v46, v[54:57] offset:9216
	s_waitcnt vmcnt(2)
	ds_write_b128 v46, v[38:41] offset:13824
	s_waitcnt vmcnt(1)
	ds_write_b128 v46, v[62:65] offset:18432
	s_waitcnt vmcnt(0)
	ds_write_b128 v46, v[42:45] offset:23040
	v_mfma_f32_32x32x16_bf16 v[2:17], v[72:75], v[58:61], v[2:17]
	s_waitcnt lgkmcnt(0)
	s_barrier
	ds_read_b128 v[34:37], v0 offset:9216
	ds_read_b128 v[38:41], v48
	ds_read_b128 v[42:45], v48 offset:32
	ds_read_b128 v[50:53], v0 offset:9248
	s_waitcnt lgkmcnt(2)
	v_mfma_f32_32x32x16_bf16 v[18:33], v[34:37], v[38:41], v[18:33]
	ds_read_b128 v[34:37], v0 offset:13824
	ds_read_b128 v[54:57], v0 offset:13856
	s_waitcnt lgkmcnt(1)
	v_mfma_f32_32x32x16_bf16 v[2:17], v[34:37], v[38:41], v[2:17]
	v_mfma_f32_32x32x16_bf16 v[18:33], v[50:53], v[42:45], v[18:33]
	s_waitcnt lgkmcnt(0)
	v_mfma_f32_32x32x16_bf16 v[2:17], v[54:57], v[42:45], v[2:17]
	ds_read_b128 v[34:37], v0 offset:9280
	ds_read_b128 v[38:41], v48 offset:64
	ds_read_b128 v[42:45], v48 offset:96
	ds_read_b128 v[46:49], v0 offset:9312
	s_waitcnt lgkmcnt(2)
	v_mfma_f32_32x32x16_bf16 v[18:33], v[34:37], v[38:41], v[18:33]
	ds_read_b128 v[34:37], v0 offset:13888
	ds_read_b128 v[50:53], v0 offset:13920
	s_waitcnt lgkmcnt(0)
	s_barrier
	s_barrier
	v_mfma_f32_32x32x16_bf16 v[2:17], v[34:37], v[38:41], v[2:17]
	v_mfma_f32_32x32x16_bf16 v[18:33], v[46:49], v[42:45], v[18:33]
	v_mfma_f32_32x32x16_bf16 v[2:17], v[50:53], v[42:45], v[2:17]
	s_and_saveexec_b64 s[8:9], s[38:39]
	s_cbranch_execz .LBB0_1470
	v_add_u32_e32 v36, s72, v92
	v_lshlrev_b32_e32 v42, 5, v36
	s_movk_i32 s10, 0x1ff
	v_bitop3_b32 v43, v42, s10, v93 bitop3:0xc8
	v_lshl_add_u32 v0, v43, 8, v223
	v_cmp_eq_u32_e32 vcc, s10, v43
	v_readlane_b32 s0, v244, 3
	v_bfe_i32 v36, v36, 5, 22
	v_cndmask_b32_e64 v0, v0, 0, vcc
	v_lshlrev_b32_e32 v0, 2, v0
	v_readlane_b32 s1, v244, 4
	v_ashrrev_i32_e32 v37, 31, v36
	v_lshlrev_b64 v[36:37], 19, v[36:37]
	v_lshl_add_u64 v[34:35], s[0:1], 0, v[0:1]
	v_lshl_add_u64 v[34:35], v[34:35], 0, v[36:37]
	v_lshlrev_b32_e32 v0, 2, v66
	v_lshl_add_u64 v[38:39], v[34:35], 0, v[0:1]
	global_load_dwordx4 v[34:37], v[38:39], off
	s_nop 0
	global_load_dwordx4 v[38:41], v[38:39], off offset:32
	v_cmp_ne_u32_e64 s[0:1], s10, v43
	v_mov_b32_e32 v44, 0
	v_mov_b32_e32 v47, 0
	v_mov_b32_e32 v49, 0
	v_mov_b32_e32 v46, 0
	s_and_saveexec_b64 s[10:11], s[0:1]
	s_cbranch_execz .LBB0_1526
	s_waitcnt vmcnt(0)
	v_pk_mul_f32 v[48:49], v[24:25], v[40:41]
	v_pk_mul_f32 v[50:51], v[18:19], v[38:39]
	v_pk_fma_f32 v[48:49], v[20:21], v[36:37], v[48:49] neg_lo:[0,0,1] neg_hi:[0,0,1]
	v_pk_fma_f32 v[50:51], v[22:23], v[34:35], v[50:51]
	v_cvt_pk_bf16_f32 v49, v48, v49
	v_cvt_pk_bf16_f32 v46, v50, v51

; DI void phase_final(const bf16_t* __restrict__ h16, float* __restrict__ out, const float* __restrict__ g) {
;     ...
;     for (int row = wv; row < T_; row += nw) {
;         const uint2* hp = (const uint2*)(h16 + (size_t)row * 1024);
;         float4 v[4];
;         float ss = 0.f;
; #pragma unroll
;         for (int i = 0; i < 4; ++i) {
;             const uint2 u = hp[lane + 64 * i];
;             v[i].x = __uint_as_float(u.x << 16); v[i].y = __uint_as_float(u.x & 0xffff0000u);
;             v[i].z = __uint_as_float(u.y << 16); v[i].w = __uint_as_float(u.y & 0xffff0000u);
;             ss += v[i].x * v[i].x + v[i].y * v[i].y + v[i].z * v[i].z + v[i].w * v[i].w;
;         }
;         ss = wave_sum(ss);
;         const float rstd = rsqrtf(ss * (1.f / 1024.f) + 1e-5f);
; #pragma unroll
;         for (int i = 0; i < 4; ++i) {
;             const float4 gg = ((const float4*)g)[lane + 64 * i];
;             float4 o;
;             o.x = v[i].x * rstd * gg.x; o.y = v[i].y * rstd * gg.y; o.z = v[i].z * rstd * gg.z; o.w = v[i].w * rstd * gg.w;
;             ((float4*)(out + (size_t)row * 1024))[lane + 64 * i] = o;
;         }
;     }
.LBB0_1779:
	global_load_dwordx2 v[28:29], v[18:19], off
	global_load_dwordx2 v[50:51], v[18:19], off offset:512
	global_load_dwordx2 v[52:53], v[18:19], off offset:1024
	global_load_dwordx2 v[54:55], v[18:19], off offset:1536
	v_add_u32_e32 v0, s8, v0
	s_movk_i32 s9, 0x7fff
	v_lshl_add_u64 v[18:19], v[18:19], 0, s[10:11]
	s_waitcnt vmcnt(0)
	v_lshlrev_b32_e32 v30, 16, v28
	v_and_b32_e32 v31, 0xffff0000, v28
	v_lshlrev_b32_e32 v32, 16, v29
	v_and_b32_e32 v33, 0xffff0000, v29
	v_mul_f32_e32 v46, v33, v33
	v_lshlrev_b32_e32 v34, 16, v50
	v_and_b32_e32 v35, 0xffff0000, v50
	v_lshlrev_b32_e32 v36, 16, v51
	v_and_b32_e32 v37, 0xffff0000, v51
	v_mul_f32_e32 v48, v37, v37
	v_lshlrev_b32_e32 v38, 16, v52
	v_and_b32_e32 v39, 0xffff0000, v52
	v_lshlrev_b32_e32 v40, 16, v53
	v_and_b32_e32 v41, 0xffff0000, v53
	v_lshlrev_b32_e32 v42, 16, v54
	v_and_b32_e32 v43, 0xffff0000, v54
	v_mul_f32_e32 v28, v31, v31
	v_lshlrev_b32_e32 v44, 16, v55
	v_and_b32_e32 v45, 0xffff0000, v55
	v_pk_fma_f32 v[28:29], v[30:31], v[30:31], v[28:29] op_sel_hi:[1,1,0]
	s_nop 0
	v_pk_fma_f32 v[28:29], v[32:33], v[32:33], v[28:29]
	s_nop 0
	v_pk_add_f32 v[28:29], v[46:47], v[28:29] op_sel_hi:[0,1]
	v_mul_f32_e32 v46, v35, v35
	v_pk_fma_f32 v[46:47], v[34:35], v[34:35], v[46:47] op_sel_hi:[1,1,0]
	s_nop 0
	v_pk_fma_f32 v[46:47], v[36:37], v[36:37], v[46:47]
	s_nop 0
	v_pk_add_f32 v[46:47], v[48:49], v[46:47] op_sel_hi:[0,1]
	v_pk_add_f32 v[28:29], v[28:29], v[46:47]
	v_mul_f32_e32 v46, v39, v39
	v_pk_fma_f32 v[46:47], v[38:39], v[38:39], v[46:47] op_sel_hi:[1,1,0]
	v_mul_f32_e32 v48, v41, v41
	v_pk_fma_f32 v[46:47], v[40:41], v[40:41], v[46:47]
	s_nop 0
	v_pk_add_f32 v[46:47], v[48:49], v[46:47] op_sel_hi:[0,1]
	v_pk_add_f32 v[28:29], v[28:29], v[46:47]
	v_mul_f32_e32 v46, v43, v43
	v_pk_fma_f32 v[46:47], v[42:43], v[42:43], v[46:47] op_sel_hi:[1,1,0]
	v_mul_f32_e32 v48, v45, v45
	v_pk_fma_f32 v[46:47], v[44:45], v[44:45], v[46:47]
	s_nop 0
	v_pk_add_f32 v[46:47], v[48:49], v[46:47] op_sel_hi:[0,1]
	v_pk_add_f32 v[28:29], v[28:29], v[46:47]
	s_nop 0
	v_mov_b32_e32 v27, v28
	s_nop 1
	v_permlane32_swap_b32_e32 v28, v27
	v_add_f32_e32 v27, v28, v27
	ds_bpermute_b32 v28, v22, v27
	s_waitcnt lgkmcnt(0)
	v_add_f32_e32 v27, v27, v28
	ds_bpermute_b32 v28, v23, v27
	s_waitcnt lgkmcnt(0)
	v_add_f32_e32 v27, v27, v28
	ds_bpermute_b32 v28, v24, v27
	s_waitcnt lgkmcnt(0)
	v_add_f32_e32 v27, v27, v28
	ds_bpermute_b32 v28, v25, v27
	s_waitcnt lgkmcnt(0)
	v_add_f32_e32 v27, v27, v28
	ds_bpermute_b32 v28, v26, v27
	s_waitcnt lgkmcnt(0)
	v_add_f32_e32 v27, v27, v28
	v_fmamk_f32 v27, v27, 0x3a800000, v202
	v_cmp_gt_f32_e32 vcc, s30, v27
	v_mul_f32_e32 v28, 0x4b800000, v27
	s_nop 0
	v_cndmask_b32_e32 v27, v27, v28, vcc
	v_rsq_f32_e32 v27, v27
	s_nop 0
	v_mul_f32_e32 v28, 0x45800000, v27
	v_cndmask_b32_e32 v46, v27, v28, vcc
	v_pk_mul_f32 v[28:29], v[46:47], v[30:31] op_sel_hi:[0,1]
	v_pk_mul_f32 v[30:31], v[46:47], v[32:33] op_sel_hi:[0,1]
	v_pk_mul_f32 v[28:29], v[2:3], v[28:29]
	v_pk_mul_f32 v[30:31], v[4:5], v[30:31]
	global_store_dwordx4 v[20:21], v[28:31], off
	v_cmp_lt_i32_e32 vcc, s9, v0
	s_or_b64 s[14:15], vcc, s[14:15]
	v_pk_mul_f32 v[28:29], v[46:47], v[34:35] op_sel_hi:[0,1]
	v_pk_mul_f32 v[30:31], v[46:47], v[36:37] op_sel_hi:[0,1]
	v_pk_mul_f32 v[28:29], v[6:7], v[28:29]
	v_pk_mul_f32 v[30:31], v[8:9], v[30:31]
	global_store_dwordx4 v[20:21], v[28:31], off offset:1024
	s_nop 1
	v_pk_mul_f32 v[28:29], v[46:47], v[38:39] op_sel_hi:[0,1]
	v_pk_mul_f32 v[30:31], v[46:47], v[40:41] op_sel_hi:[0,1]
	v_pk_mul_f32 v[28:29], v[10:11], v[28:29]
	v_pk_mul_f32 v[30:31], v[12:13], v[30:31]
	global_store_dwordx4 v[20:21], v[28:31], off offset:2048
	s_nop 1
	v_pk_mul_f32 v[28:29], v[46:47], v[42:43] op_sel_hi:[0,1]
	v_pk_mul_f32 v[30:31], v[46:47], v[44:45] op_sel_hi:[0,1]
	v_pk_mul_f32 v[28:29], v[14:15], v[28:29]
	v_pk_mul_f32 v[30:31], v[16:17], v[30:31]
	global_store_dwordx4 v[20:21], v[28:31], off offset:3072
	v_lshl_add_u64 v[20:21], v[20:21], 0, s[12:13]
	s_andn2_b64 exec, exec, s[14:15]
	s_cbranch_execnz .LBB0_1779
